# v29: + K-loop MFMA segments arrive at the barrier before dropping priority (s_barrier then s_setprio 0)
# speedup vs baseline: 1.0046x; 1.0015x over previous
; #define PG8_STAGE(bufoff, gbase, voff) do { _Pragma("unroll") for (int _i = 0; _i < 2; ++_i) \
;         __builtin_amdgcn_global_load_lds((const unsigned*)((const char*)(gbase) + (voff)[_i]), (PG8_LAS unsigned*)(lds + (bufoff) + ldsw + _i * 8192), 16, 0, 0); } while (0)
; #define PG8_LDA(dst, b, h) do { _Pragma("unroll") for (int m = 0; m < 4; ++m) _Pragma("unroll") for (int k = 0; k < 2; ++k) dst[m][k] = *(const PG8_LAS bf16x8*)(lds + PG8_SA(b, h) + aoff + m * 2048 + k * 1024); } while (0)
; #define PG8_LDB(dst, b, h) do { _Pragma("unroll") for (int n = 0; n < 2; ++n) _Pragma("unroll") for (int k = 0; k < 2; ++k) dst[n][k] = *(const PG8_LAS bf16x8*)(lds + PG8_SB(b, h) + boff + n * 2048 + k * 1024); } while (0)
; #define PG8_MMA(ai, bj, At, Bt) do { __builtin_amdgcn_s_setprio(1); _Pragma("unroll") for (int m = 0; m < 4; ++m) _Pragma("unroll") for (int n = 0; n < 2; ++n) _Pragma("unroll") for (int k = 0; k < 2; ++k) \
;         acc[ai][bj][m][n] = __builtin_amdgcn_mfma_f32_16x16x32_bf16(Bt[n][k], At[m][k], acc[ai][bj][m][n], 0, 0, 0); __builtin_amdgcn_s_setprio(0); } while (0)
; #define PG8_WAIT_V(n) asm volatile("s_waitcnt vmcnt(" #n ")" ::: "memory")
; #define PG8_WAIT_L(n) asm volatile("s_waitcnt lgkmcnt(" #n ")" ::: "memory")
; template <class Epi, class Sched, bool ALIGN_EPI = false, bool SP2 = false>
; __device__ __forceinline__ void gemm_phase(PG8_LAS unsigned char* lds, const Gemm g, const Sched& S, const Epi& E, const int wave_s) {
;     ...
;             const bool last = (t == nt - 2);
;             const char* a1 = cA + (size_t)(t + 1) * kstep;
;             const char* a2 = last ? nA : cA + (size_t)(t + 2) * kstep; const char* b2 = last ? nB : cB + (size_t)(t + 2) * kstep;
;             const char* a3 = a2 + kstep; const char* b3 = b2 + kstep;
;             if (last && has_next) S.a_ready(nxt);
;             if constexpr (SP2) {
;             PG8_LDB(B0, 0, 0); PG8_LDB(B1, 0, 1); PG8_SCHED; PG8_LDA(At, 0, 0); PG8_STAGE(PG8_SA(1, 1), a1 + hstep, voffA);
;             PG8_WAIT_V(8); PG8_WAIT_L(0); PG8_BAR; PG8_MMA(0, 0, At, B0); PG8_MMA(0, 1, At, B1); PG8_BAR; PG8_SCHED;
;             PG8_LDA(At, 0, 1); PG8_STAGE(PG8_SB(0, 0), b2, voffB); PG8_STAGE(PG8_SB(0, 1), b2 + hstep, voffB); PG8_STAGE(PG8_SA(0, 0), a2, voffA);
;             PG8_WAIT_V(8); PG8_WAIT_L(0); PG8_BAR; PG8_MMA(1, 0, At, B0); PG8_MMA(1, 1, At, B1); PG8_BAR; PG8_SCHED;
.LBB0_219:
	s_add_u32 s34, s30, 0xfffc0080
	s_addc_u32 s35, s31, -1
	s_add_i32 s45, 0, 0x10000
	s_cmp_eq_u32 s68, 12
	s_cselect_b32 s37, s5, s35
	s_cselect_b32 s36, s23, s34
	v_add_u32_e32 v0, s45, v180
	s_cselect_b32 s35, s21, s64
	s_cselect_b32 s34, s29, s55
	s_add_i32 s75, 0, 0x14000
	ds_read_b128 v[78:81], v0
	ds_read_b128 v[86:89], v0 offset:1024
	ds_read_b128 v[98:101], v0 offset:2048
	ds_read_b128 v[102:105], v0 offset:3072
	v_add_u32_e32 v0, s75, v180
	ds_read_b128 v[170:173], v0
	ds_read_b128 v[174:177], v0 offset:1024
	ds_read_b128 v[184:187], v0 offset:2048
	ds_read_b128 v[188:191], v0 offset:3072
	v_lshl_add_u64 v[230:231], s[30:31], 0, v[164:165]
	s_add_i32 m0, s47, 0xc000
	ds_read_b128 v[192:195], v182
	ds_read_b128 v[196:199], v182 offset:1024
	ds_read_b128 v[200:203], v182 offset:2048
	ds_read_b128 v[210:213], v182 offset:3072
	ds_read_b128 v[214:217], v182 offset:4096
	ds_read_b128 v[218:221], v182 offset:5120
	ds_read_b128 v[222:225], v182 offset:6144
	ds_read_b128 v[226:229], v182 offset:7168
	global_load_lds_dwordx4 v[230:231], off
	v_lshl_add_u64 v[230:231], s[30:31], 0, v[166:167]
	s_add_i32 m0, s47, 0xe000
	s_nop 0
	global_load_lds_dwordx4 v[230:231], off
	s_waitcnt vmcnt(8)
	s_waitcnt lgkmcnt(0)
	s_barrier
	s_setprio 1
	v_mfma_f32_16x16x32_bf16 v[142:145], v[78:81], v[192:195], v[142:145]
	v_mfma_f32_16x16x32_bf16 v[138:141], v[98:101], v[192:195], v[138:141]
	v_mfma_f32_16x16x32_bf16 v[126:129], v[78:81], v[200:203], v[126:129]
	v_mfma_f32_16x16x32_bf16 v[122:125], v[98:101], v[200:203], v[122:125]
	v_mfma_f32_16x16x32_bf16 v[110:113], v[78:81], v[214:217], v[110:113]
	v_mfma_f32_16x16x32_bf16 v[106:109], v[98:101], v[214:217], v[106:109]
	v_mfma_f32_16x16x32_bf16 v[82:85], v[78:81], v[222:225], v[82:85]
	v_mfma_f32_16x16x32_bf16 v[74:77], v[98:101], v[222:225], v[74:77]
	v_mfma_f32_16x16x32_bf16 v[142:145], v[86:89], v[196:199], v[142:145]
	v_mfma_f32_16x16x32_bf16 v[138:141], v[102:105], v[196:199], v[138:141]
	v_mfma_f32_16x16x32_bf16 v[126:129], v[86:89], v[210:213], v[126:129]
	v_mfma_f32_16x16x32_bf16 v[122:125], v[102:105], v[210:213], v[122:125]
	v_mfma_f32_16x16x32_bf16 v[110:113], v[86:89], v[218:221], v[110:113]
	v_mfma_f32_16x16x32_bf16 v[106:109], v[102:105], v[218:221], v[106:109]
	v_mfma_f32_16x16x32_bf16 v[82:85], v[86:89], v[226:229], v[82:85]
	v_mfma_f32_16x16x32_bf16 v[74:77], v[102:105], v[226:229], v[74:77]
	s_setprio 0
	s_setprio 1
	v_mfma_f32_16x16x32_bf16 v[134:137], v[170:173], v[192:195], v[134:137]
	v_mfma_f32_16x16x32_bf16 v[130:133], v[184:187], v[192:195], v[130:133]
	v_mfma_f32_16x16x32_bf16 v[118:121], v[170:173], v[200:203], v[118:121]
	v_mfma_f32_16x16x32_bf16 v[114:117], v[184:187], v[200:203], v[114:117]
	v_mfma_f32_16x16x32_bf16 v[94:97], v[170:173], v[214:217], v[94:97]
	v_mfma_f32_16x16x32_bf16 v[90:93], v[184:187], v[214:217], v[90:93]
	v_mfma_f32_16x16x32_bf16 v[70:73], v[170:173], v[222:225], v[70:73]
	v_mfma_f32_16x16x32_bf16 v[66:69], v[184:187], v[222:225], v[66:69]
	v_mfma_f32_16x16x32_bf16 v[134:137], v[174:177], v[196:199], v[134:137]
	v_mfma_f32_16x16x32_bf16 v[130:133], v[188:191], v[196:199], v[130:133]
	v_mfma_f32_16x16x32_bf16 v[118:121], v[174:177], v[210:213], v[118:121]
	v_mfma_f32_16x16x32_bf16 v[114:117], v[188:191], v[210:213], v[114:117]
	v_mfma_f32_16x16x32_bf16 v[94:97], v[174:177], v[218:221], v[94:97]
	v_mfma_f32_16x16x32_bf16 v[90:93], v[188:191], v[218:221], v[90:93]
	v_mfma_f32_16x16x32_bf16 v[70:73], v[174:177], v[226:229], v[70:73]
	v_mfma_f32_16x16x32_bf16 v[66:69], v[188:191], v[226:229], v[66:69]
	s_barrier
	s_setprio 0
	s_add_i32 s45, s45, s44
	v_lshl_add_u64 v[230:231], s[34:35], 0, v[148:149]
	s_mov_b32 m0, s45
	ds_read_b128 v[192:195], v182 offset:16384
	ds_read_b128 v[196:199], v182 offset:17408
	ds_read_b128 v[200:203], v182 offset:18432
	ds_read_b128 v[210:213], v182 offset:19456
	ds_read_b128 v[214:217], v182 offset:20480
	ds_read_b128 v[218:221], v182 offset:21504
	ds_read_b128 v[222:225], v182 offset:22528
	ds_read_b128 v[226:229], v182 offset:23552
	global_load_lds_dwordx4 v[230:231], off
	s_add_i32 m0, s45, 0x2000
	s_add_u32 s80, s34, 0x40000
	v_lshl_add_u64 v[232:233], s[34:35], 0, v[152:153]
	s_addc_u32 s81, s35, 0
	s_add_i32 s45, s75, s44
	global_load_lds_dwordx4 v[232:233], off
	v_lshl_add_u64 v[234:235], s[80:81], 0, v[148:149]
	s_mov_b32 m0, s45
	v_lshl_add_u64 v[236:237], s[36:37], 0, v[150:151]
	global_load_lds_dwordx4 v[234:235], off
	v_lshl_add_u64 v[234:235], s[80:81], 0, v[152:153]
	s_add_i32 m0, s45, 0x2000
	s_nop 0
	global_load_lds_dwordx4 v[234:235], off
	v_lshl_add_u64 v[234:235], s[36:37], 0, v[146:147]
	s_mov_b32 m0, s47
	s_nop 0
	global_load_lds_dwordx4 v[234:235], off
	s_mov_b32 m0, s48
	s_nop 0
	global_load_lds_dwordx4 v[236:237], off
	s_waitcnt vmcnt(8)
	s_waitcnt lgkmcnt(0)
	s_barrier
; #define PG8_STAGE(bufoff, gbase, voff) do { _Pragma("unroll") for (int _i = 0; _i < 2; ++_i) \
;         __builtin_amdgcn_global_load_lds((const unsigned*)((const char*)(gbase) + (voff)[_i]), (PG8_LAS unsigned*)(lds + (bufoff) + ldsw + _i * 8192), 16, 0, 0); } while (0)
; #define PG8_LDA(dst, b, h) do { _Pragma("unroll") for (int m = 0; m < 4; ++m) _Pragma("unroll") for (int k = 0; k < 2; ++k) dst[m][k] = *(const PG8_LAS bf16x8*)(lds + PG8_SA(b, h) + aoff + m * 2048 + k * 1024); } while (0)
; #define PG8_LDB(dst, b, h) do { _Pragma("unroll") for (int n = 0; n < 2; ++n) _Pragma("unroll") for (int k = 0; k < 2; ++k) dst[n][k] = *(const PG8_LAS bf16x8*)(lds + PG8_SB(b, h) + boff + n * 2048 + k * 1024); } while (0)
; #define PG8_MMA(ai, bj, At, Bt) do { __builtin_amdgcn_s_setprio(1); _Pragma("unroll") for (int m = 0; m < 4; ++m) _Pragma("unroll") for (int n = 0; n < 2; ++n) _Pragma("unroll") for (int k = 0; k < 2; ++k) \
;         acc[ai][bj][m][n] = __builtin_amdgcn_mfma_f32_16x16x32_bf16(Bt[n][k], At[m][k], acc[ai][bj][m][n], 0, 0, 0); __builtin_amdgcn_s_setprio(0); } while (0)
; #define PG8_WAIT_V(n) asm volatile("s_waitcnt vmcnt(" #n ")" ::: "memory")
; #define PG8_WAIT_L(n) asm volatile("s_waitcnt lgkmcnt(" #n ")" ::: "memory")
; #define PG8_BAR __builtin_amdgcn_s_barrier()
; #define PG8_SCHED __builtin_amdgcn_sched_barrier(0)
; template <class Epi, class Sched, bool ALIGN_EPI = false, bool SP2 = false>
; __device__ __forceinline__ void gemm_phase(PG8_LAS unsigned char* lds, const Gemm g, const Sched& S, const Epi& E, const int wave_s) {
;     ...
;             PG8_WAIT_V(8); PG8_WAIT_L(0); PG8_BAR; PG8_MMA(1, 0, At, B0); PG8_MMA(1, 1, At, B1); PG8_BAR; PG8_SCHED;
;             PG8_LDB(B0, 1, 0); PG8_LDB(B1, 1, 1); PG8_SCHED; PG8_LDA(At, 1, 0); PG8_STAGE(PG8_SA(0, 1), a2 + hstep, voffA);
;             PG8_WAIT_V(8); PG8_WAIT_L(0); PG8_BAR; PG8_MMA(0, 0, At, B0); PG8_MMA(0, 1, At, B1); PG8_BAR; PG8_SCHED;
	s_setprio 1
	v_mfma_f32_16x16x32_bf16 v[62:65], v[78:81], v[192:195], v[62:65]
	v_mfma_f32_16x16x32_bf16 v[58:61], v[98:101], v[192:195], v[58:61]
	v_mfma_f32_16x16x32_bf16 v[46:49], v[78:81], v[200:203], v[46:49]
	v_mfma_f32_16x16x32_bf16 v[42:45], v[98:101], v[200:203], v[42:45]
	v_mfma_f32_16x16x32_bf16 v[30:33], v[78:81], v[214:217], v[30:33]
	v_mfma_f32_16x16x32_bf16 v[26:29], v[98:101], v[214:217], v[26:29]
	v_mfma_f32_16x16x32_bf16 v[14:17], v[78:81], v[222:225], v[14:17]
	v_mfma_f32_16x16x32_bf16 v[10:13], v[98:101], v[222:225], v[10:13]
	v_mfma_f32_16x16x32_bf16 v[62:65], v[86:89], v[196:199], v[62:65]
	v_mfma_f32_16x16x32_bf16 v[58:61], v[102:105], v[196:199], v[58:61]
	v_mfma_f32_16x16x32_bf16 v[46:49], v[86:89], v[210:213], v[46:49]
	v_mfma_f32_16x16x32_bf16 v[42:45], v[102:105], v[210:213], v[42:45]
	v_mfma_f32_16x16x32_bf16 v[30:33], v[86:89], v[218:221], v[30:33]
	v_mfma_f32_16x16x32_bf16 v[26:29], v[102:105], v[218:221], v[26:29]
	v_mfma_f32_16x16x32_bf16 v[14:17], v[86:89], v[226:229], v[14:17]
	v_mfma_f32_16x16x32_bf16 v[10:13], v[102:105], v[226:229], v[10:13]
	s_setprio 0
	s_setprio 1
	v_mfma_f32_16x16x32_bf16 v[54:57], v[170:173], v[192:195], v[54:57]
	v_mfma_f32_16x16x32_bf16 v[50:53], v[184:187], v[192:195], v[50:53]
	v_mfma_f32_16x16x32_bf16 v[38:41], v[170:173], v[200:203], v[38:41]
	v_mfma_f32_16x16x32_bf16 v[34:37], v[184:187], v[200:203], v[34:37]
	v_mfma_f32_16x16x32_bf16 v[22:25], v[170:173], v[214:217], v[22:25]
	v_mfma_f32_16x16x32_bf16 v[18:21], v[184:187], v[214:217], v[18:21]
	v_mfma_f32_16x16x32_bf16 v[6:9], v[170:173], v[222:225], v[6:9]
	v_mfma_f32_16x16x32_bf16 v[2:5], v[184:187], v[222:225], v[2:5]
	v_mfma_f32_16x16x32_bf16 v[54:57], v[174:177], v[196:199], v[54:57]
	v_mfma_f32_16x16x32_bf16 v[50:53], v[188:191], v[196:199], v[50:53]
	v_mfma_f32_16x16x32_bf16 v[38:41], v[174:177], v[210:213], v[38:41]
	v_mfma_f32_16x16x32_bf16 v[34:37], v[188:191], v[210:213], v[34:37]
	v_mfma_f32_16x16x32_bf16 v[22:25], v[174:177], v[218:221], v[22:25]
	v_mfma_f32_16x16x32_bf16 v[18:21], v[188:191], v[218:221], v[18:21]
	v_mfma_f32_16x16x32_bf16 v[6:9], v[174:177], v[226:229], v[6:9]
	v_mfma_f32_16x16x32_bf16 v[2:5], v[188:191], v[226:229], v[2:5]
	s_barrier
	s_setprio 0
	s_add_i32 s45, 0, 0x18000
	v_add_u32_e32 v0, s45, v180
	s_add_i32 s75, 0, 0x1c000
	ds_read_b128 v[78:81], v0
	ds_read_b128 v[86:89], v0 offset:1024
	ds_read_b128 v[98:101], v0 offset:2048
	ds_read_b128 v[102:105], v0 offset:3072
	v_add_u32_e32 v0, s75, v180
	ds_read_b128 v[170:173], v0
	ds_read_b128 v[174:177], v0 offset:1024
	ds_read_b128 v[184:187], v0 offset:2048
	ds_read_b128 v[188:191], v0 offset:3072
	s_add_u32 s36, s36, 0x40000
	s_addc_u32 s37, s37, 0
	s_mov_b32 m0, s49
	v_lshl_add_u64 v[238:239], s[36:37], 0, v[146:147]
	ds_read_b128 v[192:195], v182 offset:32768
	ds_read_b128 v[196:199], v182 offset:33792
	ds_read_b128 v[200:203], v182 offset:34816
	ds_read_b128 v[210:213], v182 offset:35840
	ds_read_b128 v[214:217], v182 offset:36864
	ds_read_b128 v[218:221], v182 offset:37888
	ds_read_b128 v[222:225], v182 offset:38912
	ds_read_b128 v[226:229], v182 offset:39936
	global_load_lds_dwordx4 v[238:239], off
	v_lshl_add_u64 v[238:239], s[36:37], 0, v[150:151]
	s_mov_b32 m0, s50
	s_nop 0
	global_load_lds_dwordx4 v[238:239], off
	s_waitcnt vmcnt(8)
	s_waitcnt lgkmcnt(0)
	s_barrier
	s_setprio 1
	v_mfma_f32_16x16x32_bf16 v[142:145], v[78:81], v[192:195], v[142:145]
	v_mfma_f32_16x16x32_bf16 v[138:141], v[98:101], v[192:195], v[138:141]
	v_mfma_f32_16x16x32_bf16 v[126:129], v[78:81], v[200:203], v[126:129]
	v_mfma_f32_16x16x32_bf16 v[122:125], v[98:101], v[200:203], v[122:125]
	v_mfma_f32_16x16x32_bf16 v[110:113], v[78:81], v[214:217], v[110:113]
	v_mfma_f32_16x16x32_bf16 v[106:109], v[98:101], v[214:217], v[106:109]
	v_mfma_f32_16x16x32_bf16 v[82:85], v[78:81], v[222:225], v[82:85]
	v_mfma_f32_16x16x32_bf16 v[74:77], v[98:101], v[222:225], v[74:77]
	v_mfma_f32_16x16x32_bf16 v[142:145], v[86:89], v[196:199], v[142:145]
	v_mfma_f32_16x16x32_bf16 v[138:141], v[102:105], v[196:199], v[138:141]
	v_mfma_f32_16x16x32_bf16 v[126:129], v[86:89], v[210:213], v[126:129]
	v_mfma_f32_16x16x32_bf16 v[122:125], v[102:105], v[210:213], v[122:125]
	v_mfma_f32_16x16x32_bf16 v[110:113], v[86:89], v[218:221], v[110:113]
	v_mfma_f32_16x16x32_bf16 v[106:109], v[102:105], v[218:221], v[106:109]
	v_mfma_f32_16x16x32_bf16 v[82:85], v[86:89], v[226:229], v[82:85]
	v_mfma_f32_16x16x32_bf16 v[74:77], v[102:105], v[226:229], v[74:77]
	s_setprio 0
	s_setprio 1
	v_mfma_f32_16x16x32_bf16 v[134:137], v[170:173], v[192:195], v[134:137]
	v_mfma_f32_16x16x32_bf16 v[130:133], v[184:187], v[192:195], v[130:133]
	v_mfma_f32_16x16x32_bf16 v[118:121], v[170:173], v[200:203], v[118:121]
	v_mfma_f32_16x16x32_bf16 v[114:117], v[184:187], v[200:203], v[114:117]
	v_mfma_f32_16x16x32_bf16 v[94:97], v[170:173], v[214:217], v[94:97]
	v_mfma_f32_16x16x32_bf16 v[90:93], v[184:187], v[214:217], v[90:93]
	v_mfma_f32_16x16x32_bf16 v[70:73], v[170:173], v[222:225], v[70:73]
	v_mfma_f32_16x16x32_bf16 v[66:69], v[184:187], v[222:225], v[66:69]
	v_mfma_f32_16x16x32_bf16 v[134:137], v[174:177], v[196:199], v[134:137]
	v_mfma_f32_16x16x32_bf16 v[130:133], v[188:191], v[196:199], v[130:133]
	v_mfma_f32_16x16x32_bf16 v[118:121], v[174:177], v[210:213], v[118:121]
	v_mfma_f32_16x16x32_bf16 v[114:117], v[188:191], v[210:213], v[114:117]
	v_mfma_f32_16x16x32_bf16 v[94:97], v[174:177], v[218:221], v[94:97]
	v_mfma_f32_16x16x32_bf16 v[90:93], v[188:191], v[218:221], v[90:93]
	v_mfma_f32_16x16x32_bf16 v[70:73], v[174:177], v[226:229], v[70:73]
	v_mfma_f32_16x16x32_bf16 v[66:69], v[188:191], v[226:229], v[66:69]
	s_barrier
; #define PG8_STAGE(bufoff, gbase, voff) do { _Pragma("unroll") for (int _i = 0; _i < 2; ++_i) \
;         __builtin_amdgcn_global_load_lds((const unsigned*)((const char*)(gbase) + (voff)[_i]), (PG8_LAS unsigned*)(lds + (bufoff) + ldsw + _i * 8192), 16, 0, 0); } while (0)
; #define PG8_LDA(dst, b, h) do { _Pragma("unroll") for (int m = 0; m < 4; ++m) _Pragma("unroll") for (int k = 0; k < 2; ++k) dst[m][k] = *(const PG8_LAS bf16x8*)(lds + PG8_SA(b, h) + aoff + m * 2048 + k * 1024); } while (0)
; #define PG8_BAR __builtin_amdgcn_s_barrier()
; template <class Epi, class Sched, bool ALIGN_EPI = false, bool SP2 = false>
; __device__ __forceinline__ void gemm_phase(PG8_LAS unsigned char* lds, const Gemm g, const Sched& S, const Epi& E, const int wave_s) {
;     ...
;             PG8_LDA(At, 1, 1); PG8_STAGE(PG8_SB(1, 0), b3, voffB); PG8_STAGE(PG8_SB(1, 1), b3 + hstep, voffB); PG8_STAGE(PG8_SA(1, 0), a3, voffA);
;             PG8_WAIT_V(8); PG8_WAIT_L(0); PG8_BAR; PG8_MMA(1, 0, At, B0); PG8_MMA(1, 1, At, B1); PG8_BAR; PG8_SCHED;
;             } else {
;             PG8_LDB(B0, 0, 0); PG8_SCHED; PG8_LDA(At, 0, 0); PG8_STAGE(PG8_SA(1, 1), a1 + hstep, voffA);
;             PG8_WAIT_L(8); PG8_BAR; PG8_WAIT_L(0); PG8_MMA(0, 0, At, B0); PG8_BAR; PG8_SCHED;
;             PG8_LDB(B1, 0, 1); PG8_STAGE(PG8_SB(0, 0), b2, voffB);
;             PG8_BAR; PG8_WAIT_L(0); PG8_MMA(0, 1, At, B1); PG8_BAR;
;             PG8_LDA(At, 0, 1); PG8_STAGE(PG8_SA(0, 0), a2, voffA);
;             PG8_BAR; PG8_WAIT_L(0); PG8_MMA(1, 0, At, B0); PG8_BAR; PG8_SCHED;
;             PG8_STAGE(PG8_SB(0, 1), b2 + hstep, voffB);
;             PG8_WAIT_V(6); PG8_BAR; PG8_MMA(1, 1, At, B1); PG8_BAR;
;             PG8_LDB(B0, 1, 0); PG8_SCHED; PG8_LDA(At, 1, 0); PG8_STAGE(PG8_SA(0, 1), a2 + hstep, voffA);
;             PG8_WAIT_L(8); PG8_BAR; PG8_WAIT_L(0); PG8_MMA(0, 0, At, B0); PG8_BAR; PG8_SCHED;
;             PG8_LDB(B1, 1, 1); PG8_STAGE(PG8_SB(1, 0), b3, voffB);
;             PG8_BAR; PG8_WAIT_L(0); PG8_MMA(0, 1, At, B1); PG8_BAR;
;             PG8_LDA(At, 1, 1); PG8_STAGE(PG8_SA(1, 0), a3, voffA);
;             PG8_BAR; PG8_WAIT_L(0); PG8_MMA(1, 0, At, B0); PG8_BAR; PG8_SCHED;
;             PG8_STAGE(PG8_SB(1, 1), b3 + hstep, voffB);
;             PG8_WAIT_V(6); PG8_BAR; PG8_MMA(1, 1, At, B1); PG8_BAR;
;             }
;         }
;         if constexpr (ALIGN_EPI) { if (wr == 0) PG8_BAR; }
	s_setprio 0
	s_add_i32 s36, s45, s44
	v_lshl_add_u64 v[230:231], v[230:231], 0, s[70:71]
	s_mov_b32 m0, s36
	ds_read_b128 v[192:195], v182 offset:49152
	ds_read_b128 v[196:199], v182 offset:50176
	ds_read_b128 v[200:203], v182 offset:51200
	ds_read_b128 v[210:213], v182 offset:52224
	ds_read_b128 v[214:217], v182 offset:53248
	ds_read_b128 v[218:221], v182 offset:54272
	ds_read_b128 v[222:225], v182 offset:55296
	ds_read_b128 v[226:229], v182 offset:56320
	global_load_lds_dwordx4 v[230:231], off
	s_add_i32 m0, s36, 0x2000
	s_add_u32 s34, s34, 0x40080
	v_lshl_add_u64 v[230:231], v[232:233], 0, s[70:71]
	s_addc_u32 s35, s35, 0
	s_add_i32 s36, s75, s44
	global_load_lds_dwordx4 v[230:231], off
	v_lshl_add_u64 v[230:231], s[34:35], 0, v[148:149]
	s_mov_b32 m0, s36
	s_nop 0
	global_load_lds_dwordx4 v[230:231], off
	v_lshl_add_u64 v[230:231], s[34:35], 0, v[152:153]
	s_add_i32 m0, s36, 0x2000
	s_nop 0
	global_load_lds_dwordx4 v[230:231], off
	v_lshl_add_u64 v[230:231], v[234:235], 0, s[70:71]
	s_mov_b32 m0, s58
	s_nop 0
	global_load_lds_dwordx4 v[230:231], off
	v_lshl_add_u64 v[230:231], v[236:237], 0, s[70:71]
	s_mov_b32 m0, s59
	s_nop 0
	global_load_lds_dwordx4 v[230:231], off
	s_waitcnt vmcnt(8)
	s_waitcnt lgkmcnt(0)
	s_barrier
	s_setprio 1
	v_mfma_f32_16x16x32_bf16 v[62:65], v[78:81], v[192:195], v[62:65]
	v_mfma_f32_16x16x32_bf16 v[58:61], v[98:101], v[192:195], v[58:61]
	v_mfma_f32_16x16x32_bf16 v[46:49], v[78:81], v[200:203], v[46:49]
	v_mfma_f32_16x16x32_bf16 v[42:45], v[98:101], v[200:203], v[42:45]
	v_mfma_f32_16x16x32_bf16 v[30:33], v[78:81], v[214:217], v[30:33]
	v_mfma_f32_16x16x32_bf16 v[26:29], v[98:101], v[214:217], v[26:29]
	v_mfma_f32_16x16x32_bf16 v[14:17], v[78:81], v[222:225], v[14:17]
	v_mfma_f32_16x16x32_bf16 v[10:13], v[98:101], v[222:225], v[10:13]
	v_mfma_f32_16x16x32_bf16 v[62:65], v[86:89], v[196:199], v[62:65]
	v_mfma_f32_16x16x32_bf16 v[58:61], v[102:105], v[196:199], v[58:61]
	v_mfma_f32_16x16x32_bf16 v[46:49], v[86:89], v[210:213], v[46:49]
	v_mfma_f32_16x16x32_bf16 v[42:45], v[102:105], v[210:213], v[42:45]
	v_mfma_f32_16x16x32_bf16 v[30:33], v[86:89], v[218:221], v[30:33]
	v_mfma_f32_16x16x32_bf16 v[26:29], v[102:105], v[218:221], v[26:29]
	v_mfma_f32_16x16x32_bf16 v[14:17], v[86:89], v[226:229], v[14:17]
	v_mfma_f32_16x16x32_bf16 v[10:13], v[102:105], v[226:229], v[10:13]
	s_setprio 0
	s_setprio 1
	v_mfma_f32_16x16x32_bf16 v[54:57], v[170:173], v[192:195], v[54:57]
	v_mfma_f32_16x16x32_bf16 v[50:53], v[184:187], v[192:195], v[50:53]
	v_mfma_f32_16x16x32_bf16 v[38:41], v[170:173], v[200:203], v[38:41]
	v_mfma_f32_16x16x32_bf16 v[34:37], v[184:187], v[200:203], v[34:37]
	v_mfma_f32_16x16x32_bf16 v[22:25], v[170:173], v[214:217], v[22:25]
	v_mfma_f32_16x16x32_bf16 v[18:21], v[184:187], v[214:217], v[18:21]
	v_mfma_f32_16x16x32_bf16 v[6:9], v[170:173], v[222:225], v[6:9]
	v_mfma_f32_16x16x32_bf16 v[2:5], v[184:187], v[222:225], v[2:5]
	v_mfma_f32_16x16x32_bf16 v[54:57], v[174:177], v[196:199], v[54:57]
	v_mfma_f32_16x16x32_bf16 v[50:53], v[188:191], v[196:199], v[50:53]
	v_mfma_f32_16x16x32_bf16 v[38:41], v[174:177], v[210:213], v[38:41]
	v_mfma_f32_16x16x32_bf16 v[34:37], v[188:191], v[210:213], v[34:37]
	v_mfma_f32_16x16x32_bf16 v[22:25], v[174:177], v[218:221], v[22:25]
	v_mfma_f32_16x16x32_bf16 v[18:21], v[188:191], v[218:221], v[18:21]
	v_mfma_f32_16x16x32_bf16 v[6:9], v[174:177], v[226:229], v[6:9]
	v_mfma_f32_16x16x32_bf16 v[2:5], v[188:191], v[226:229], v[2:5]
	s_barrier
	s_setprio 0
	s_add_i32 s68, s68, 2
	s_add_u32 s30, s30, 0x100
	s_addc_u32 s31, s31, 0
	s_add_u32 s55, s55, 0x100
	s_addc_u32 s64, s64, 0
	s_cmp_gt_u32 s68, 13
	s_cbranch_scc0 .LBB0_219
	s_and_b64 vcc, exec, s[18:19]
	s_cbranch_vccz .LBB0_222
	s_barrier

; #define PG8_STAGE(bufoff, gbase, voff) do { _Pragma("unroll") for (int _i = 0; _i < 2; ++_i) \
;         __builtin_amdgcn_global_load_lds((const unsigned*)((const char*)(gbase) + (voff)[_i]), (PG8_LAS unsigned*)(lds + (bufoff) + ldsw + _i * 8192), 16, 0, 0); } while (0)
; #define PG8_LDA(dst, b, h) do { _Pragma("unroll") for (int m = 0; m < 4; ++m) _Pragma("unroll") for (int k = 0; k < 2; ++k) dst[m][k] = *(const PG8_LAS bf16x8*)(lds + PG8_SA(b, h) + aoff + m * 2048 + k * 1024); } while (0)
; #define PG8_LDB(dst, b, h) do { _Pragma("unroll") for (int n = 0; n < 2; ++n) _Pragma("unroll") for (int k = 0; k < 2; ++k) dst[n][k] = *(const PG8_LAS bf16x8*)(lds + PG8_SB(b, h) + boff + n * 2048 + k * 1024); } while (0)
; #define PG8_MMA(ai, bj, At, Bt) do { __builtin_amdgcn_s_setprio(1); _Pragma("unroll") for (int m = 0; m < 4; ++m) _Pragma("unroll") for (int n = 0; n < 2; ++n) _Pragma("unroll") for (int k = 0; k < 2; ++k) \
;         acc[ai][bj][m][n] = __builtin_amdgcn_mfma_f32_16x16x32_bf16(Bt[n][k], At[m][k], acc[ai][bj][m][n], 0, 0, 0); __builtin_amdgcn_s_setprio(0); } while (0)
; #define PG8_WAIT_V(n) asm volatile("s_waitcnt vmcnt(" #n ")" ::: "memory")
; #define PG8_WAIT_L(n) asm volatile("s_waitcnt lgkmcnt(" #n ")" ::: "memory")
; template <class Epi, class Sched, bool ALIGN_EPI = false, bool SP2 = false>
; __device__ __forceinline__ void gemm_phase(PG8_LAS unsigned char* lds, const Gemm g, const Sched& S, const Epi& E, const int wave_s) {
;     ...
;             const bool last = (t == nt - 2);
;             const char* a1 = cA + (size_t)(t + 1) * kstep;
;             const char* a2 = last ? nA : cA + (size_t)(t + 2) * kstep; const char* b2 = last ? nB : cB + (size_t)(t + 2) * kstep;
;             const char* a3 = a2 + kstep; const char* b3 = b2 + kstep;
;             if (last && has_next) S.a_ready(nxt);
;             if constexpr (SP2) {
;             PG8_LDB(B0, 0, 0); PG8_LDB(B1, 0, 1); PG8_SCHED; PG8_LDA(At, 0, 0); PG8_STAGE(PG8_SA(1, 1), a1 + hstep, voffA);
;             PG8_WAIT_V(8); PG8_WAIT_L(0); PG8_BAR; PG8_MMA(0, 0, At, B0); PG8_MMA(0, 1, At, B1); PG8_BAR; PG8_SCHED;
;             PG8_LDA(At, 0, 1); PG8_STAGE(PG8_SB(0, 0), b2, voffB); PG8_STAGE(PG8_SB(0, 1), b2 + hstep, voffB); PG8_STAGE(PG8_SA(0, 0), a2, voffA);
;             PG8_WAIT_V(8); PG8_WAIT_L(0); PG8_BAR; PG8_MMA(1, 0, At, B0); PG8_MMA(1, 1, At, B1); PG8_BAR; PG8_SCHED;
.LBB0_325:
	s_add_u32 s30, s28, 0xfffc0080
	s_addc_u32 s31, s29, -1
	s_add_i32 s45, 0, 0x10000
	s_cmp_eq_u32 s68, 12
	s_cselect_b32 s35, s19, s31
	s_cselect_b32 s34, s25, s30
	v_add_u32_e32 v0, s45, v181
	s_cselect_b32 s31, s17, s65
	s_cselect_b32 s30, s55, s64
	s_add_i32 s75, 0, 0x14000
	ds_read_b128 v[130:133], v0
	ds_read_b128 v[134:137], v0 offset:1024
	ds_read_b128 v[138:141], v0 offset:2048
	ds_read_b128 v[142:145], v0 offset:3072
	v_add_u32_e32 v0, s75, v181
	ds_read_b128 v[172:175], v0
	ds_read_b128 v[176:179], v0 offset:1024
	ds_read_b128 v[186:189], v0 offset:2048
	ds_read_b128 v[190:193], v0 offset:3072
	v_lshl_add_u64 v[202:203], s[28:29], 0, v[168:169]
	s_add_i32 m0, s27, 0xc000
	ds_read_b128 v[194:197], v185
	ds_read_b128 v[198:201], v185 offset:1024
	ds_read_b128 v[210:213], v185 offset:2048
	ds_read_b128 v[214:217], v185 offset:3072
	ds_read_b128 v[218:221], v185 offset:4096
	ds_read_b128 v[222:225], v185 offset:5120
	ds_read_b128 v[226:229], v185 offset:6144
	ds_read_b128 v[230:233], v185 offset:7168
	global_load_lds_dwordx4 v[202:203], off
	v_lshl_add_u64 v[202:203], s[28:29], 0, v[170:171]
	s_add_i32 m0, s27, 0xe000
	s_nop 0
	global_load_lds_dwordx4 v[202:203], off
	s_waitcnt vmcnt(8)
	s_waitcnt lgkmcnt(0)
	s_barrier
	s_setprio 1
	v_mfma_f32_16x16x32_bf16 v[126:129], v[130:133], v[194:197], v[126:129]
	v_mfma_f32_16x16x32_bf16 v[122:125], v[138:141], v[194:197], v[122:125]
	v_mfma_f32_16x16x32_bf16 v[110:113], v[130:133], v[210:213], v[110:113]
	v_mfma_f32_16x16x32_bf16 v[106:109], v[138:141], v[210:213], v[106:109]
	v_mfma_f32_16x16x32_bf16 v[94:97], v[130:133], v[218:221], v[94:97]
	v_mfma_f32_16x16x32_bf16 v[90:93], v[138:141], v[218:221], v[90:93]
	v_mfma_f32_16x16x32_bf16 v[78:81], v[130:133], v[226:229], v[78:81]
	v_mfma_f32_16x16x32_bf16 v[74:77], v[138:141], v[226:229], v[74:77]
	v_mfma_f32_16x16x32_bf16 v[126:129], v[134:137], v[198:201], v[126:129]
	v_mfma_f32_16x16x32_bf16 v[122:125], v[142:145], v[198:201], v[122:125]
	v_mfma_f32_16x16x32_bf16 v[110:113], v[134:137], v[214:217], v[110:113]
	v_mfma_f32_16x16x32_bf16 v[106:109], v[142:145], v[214:217], v[106:109]
	v_mfma_f32_16x16x32_bf16 v[94:97], v[134:137], v[222:225], v[94:97]
	v_mfma_f32_16x16x32_bf16 v[90:93], v[142:145], v[222:225], v[90:93]
	v_mfma_f32_16x16x32_bf16 v[78:81], v[134:137], v[230:233], v[78:81]
	v_mfma_f32_16x16x32_bf16 v[74:77], v[142:145], v[230:233], v[74:77]
	s_setprio 0
	s_setprio 1
	v_mfma_f32_16x16x32_bf16 v[118:121], v[172:175], v[194:197], v[118:121]
	v_mfma_f32_16x16x32_bf16 v[114:117], v[186:189], v[194:197], v[114:117]
	v_mfma_f32_16x16x32_bf16 v[102:105], v[172:175], v[210:213], v[102:105]
	v_mfma_f32_16x16x32_bf16 v[98:101], v[186:189], v[210:213], v[98:101]
	v_mfma_f32_16x16x32_bf16 v[86:89], v[172:175], v[218:221], v[86:89]
	v_mfma_f32_16x16x32_bf16 v[82:85], v[186:189], v[218:221], v[82:85]
	v_mfma_f32_16x16x32_bf16 v[70:73], v[172:175], v[226:229], v[70:73]
	v_mfma_f32_16x16x32_bf16 v[66:69], v[186:189], v[226:229], v[66:69]
	v_mfma_f32_16x16x32_bf16 v[118:121], v[176:179], v[198:201], v[118:121]
	v_mfma_f32_16x16x32_bf16 v[114:117], v[190:193], v[198:201], v[114:117]
	v_mfma_f32_16x16x32_bf16 v[102:105], v[176:179], v[214:217], v[102:105]
	v_mfma_f32_16x16x32_bf16 v[98:101], v[190:193], v[214:217], v[98:101]
	v_mfma_f32_16x16x32_bf16 v[86:89], v[176:179], v[222:225], v[86:89]
	v_mfma_f32_16x16x32_bf16 v[82:85], v[190:193], v[222:225], v[82:85]
	v_mfma_f32_16x16x32_bf16 v[70:73], v[176:179], v[230:233], v[70:73]
	v_mfma_f32_16x16x32_bf16 v[66:69], v[190:193], v[230:233], v[66:69]
	s_barrier
	s_setprio 0
	s_add_i32 s45, s45, s44
	v_lshl_add_u64 v[202:203], s[30:31], 0, v[148:149]
	s_mov_b32 m0, s45
	ds_read_b128 v[194:197], v185 offset:16384
	ds_read_b128 v[198:201], v185 offset:17408
	ds_read_b128 v[210:213], v185 offset:18432
	ds_read_b128 v[214:217], v185 offset:19456
	ds_read_b128 v[218:221], v185 offset:20480
	ds_read_b128 v[222:225], v185 offset:21504
	ds_read_b128 v[226:229], v185 offset:22528
	ds_read_b128 v[230:233], v185 offset:23552
	global_load_lds_dwordx4 v[202:203], off
	s_add_i32 m0, s45, 0x2000
	s_add_u32 s80, s30, 0x40000
	v_lshl_add_u64 v[234:235], s[30:31], 0, v[152:153]
	s_addc_u32 s81, s31, 0
	s_add_i32 s45, s75, s44
	global_load_lds_dwordx4 v[234:235], off
	v_lshl_add_u64 v[236:237], s[80:81], 0, v[148:149]
	s_mov_b32 m0, s45
	v_lshl_add_u64 v[238:239], s[34:35], 0, v[150:151]
	global_load_lds_dwordx4 v[236:237], off
	v_lshl_add_u64 v[236:237], s[80:81], 0, v[152:153]
	s_add_i32 m0, s45, 0x2000
	s_nop 0
	global_load_lds_dwordx4 v[236:237], off
	v_lshl_add_u64 v[236:237], s[34:35], 0, v[146:147]
	s_mov_b32 m0, s27
	s_nop 0
	global_load_lds_dwordx4 v[236:237], off
	s_mov_b32 m0, s47
	s_nop 0
	global_load_lds_dwordx4 v[238:239], off
	s_waitcnt vmcnt(8)
	s_waitcnt lgkmcnt(0)
	s_barrier
; #define PG8_STAGE(bufoff, gbase, voff) do { _Pragma("unroll") for (int _i = 0; _i < 2; ++_i) \
;         __builtin_amdgcn_global_load_lds((const unsigned*)((const char*)(gbase) + (voff)[_i]), (PG8_LAS unsigned*)(lds + (bufoff) + ldsw + _i * 8192), 16, 0, 0); } while (0)
; #define PG8_LDA(dst, b, h) do { _Pragma("unroll") for (int m = 0; m < 4; ++m) _Pragma("unroll") for (int k = 0; k < 2; ++k) dst[m][k] = *(const PG8_LAS bf16x8*)(lds + PG8_SA(b, h) + aoff + m * 2048 + k * 1024); } while (0)
; #define PG8_LDB(dst, b, h) do { _Pragma("unroll") for (int n = 0; n < 2; ++n) _Pragma("unroll") for (int k = 0; k < 2; ++k) dst[n][k] = *(const PG8_LAS bf16x8*)(lds + PG8_SB(b, h) + boff + n * 2048 + k * 1024); } while (0)
; #define PG8_MMA(ai, bj, At, Bt) do { __builtin_amdgcn_s_setprio(1); _Pragma("unroll") for (int m = 0; m < 4; ++m) _Pragma("unroll") for (int n = 0; n < 2; ++n) _Pragma("unroll") for (int k = 0; k < 2; ++k) \
;         acc[ai][bj][m][n] = __builtin_amdgcn_mfma_f32_16x16x32_bf16(Bt[n][k], At[m][k], acc[ai][bj][m][n], 0, 0, 0); __builtin_amdgcn_s_setprio(0); } while (0)
; #define PG8_WAIT_V(n) asm volatile("s_waitcnt vmcnt(" #n ")" ::: "memory")
; #define PG8_WAIT_L(n) asm volatile("s_waitcnt lgkmcnt(" #n ")" ::: "memory")
; #define PG8_BAR __builtin_amdgcn_s_barrier()
; #define PG8_SCHED __builtin_amdgcn_sched_barrier(0)
; template <class Epi, class Sched, bool ALIGN_EPI = false, bool SP2 = false>
; __device__ __forceinline__ void gemm_phase(PG8_LAS unsigned char* lds, const Gemm g, const Sched& S, const Epi& E, const int wave_s) {
;     ...
;             PG8_WAIT_V(8); PG8_WAIT_L(0); PG8_BAR; PG8_MMA(1, 0, At, B0); PG8_MMA(1, 1, At, B1); PG8_BAR; PG8_SCHED;
;             PG8_LDB(B0, 1, 0); PG8_LDB(B1, 1, 1); PG8_SCHED; PG8_LDA(At, 1, 0); PG8_STAGE(PG8_SA(0, 1), a2 + hstep, voffA);
;             PG8_WAIT_V(8); PG8_WAIT_L(0); PG8_BAR; PG8_MMA(0, 0, At, B0); PG8_MMA(0, 1, At, B1); PG8_BAR; PG8_SCHED;
	s_setprio 1
	v_mfma_f32_16x16x32_bf16 v[62:65], v[130:133], v[194:197], v[62:65]
	v_mfma_f32_16x16x32_bf16 v[58:61], v[138:141], v[194:197], v[58:61]
	v_mfma_f32_16x16x32_bf16 v[46:49], v[130:133], v[210:213], v[46:49]
	v_mfma_f32_16x16x32_bf16 v[42:45], v[138:141], v[210:213], v[42:45]
	v_mfma_f32_16x16x32_bf16 v[30:33], v[130:133], v[218:221], v[30:33]
	v_mfma_f32_16x16x32_bf16 v[26:29], v[138:141], v[218:221], v[26:29]
	v_mfma_f32_16x16x32_bf16 v[14:17], v[130:133], v[226:229], v[14:17]
	v_mfma_f32_16x16x32_bf16 v[10:13], v[138:141], v[226:229], v[10:13]
	v_mfma_f32_16x16x32_bf16 v[62:65], v[134:137], v[198:201], v[62:65]
	v_mfma_f32_16x16x32_bf16 v[58:61], v[142:145], v[198:201], v[58:61]
	v_mfma_f32_16x16x32_bf16 v[46:49], v[134:137], v[214:217], v[46:49]
	v_mfma_f32_16x16x32_bf16 v[42:45], v[142:145], v[214:217], v[42:45]
	v_mfma_f32_16x16x32_bf16 v[30:33], v[134:137], v[222:225], v[30:33]
	v_mfma_f32_16x16x32_bf16 v[26:29], v[142:145], v[222:225], v[26:29]
	v_mfma_f32_16x16x32_bf16 v[14:17], v[134:137], v[230:233], v[14:17]
	v_mfma_f32_16x16x32_bf16 v[10:13], v[142:145], v[230:233], v[10:13]
	s_setprio 0
	s_setprio 1
	v_mfma_f32_16x16x32_bf16 v[54:57], v[172:175], v[194:197], v[54:57]
	v_mfma_f32_16x16x32_bf16 v[50:53], v[186:189], v[194:197], v[50:53]
	v_mfma_f32_16x16x32_bf16 v[38:41], v[172:175], v[210:213], v[38:41]
	v_mfma_f32_16x16x32_bf16 v[34:37], v[186:189], v[210:213], v[34:37]
	v_mfma_f32_16x16x32_bf16 v[22:25], v[172:175], v[218:221], v[22:25]
	v_mfma_f32_16x16x32_bf16 v[18:21], v[186:189], v[218:221], v[18:21]
	v_mfma_f32_16x16x32_bf16 v[6:9], v[172:175], v[226:229], v[6:9]
	v_mfma_f32_16x16x32_bf16 v[2:5], v[186:189], v[226:229], v[2:5]
	v_mfma_f32_16x16x32_bf16 v[54:57], v[176:179], v[198:201], v[54:57]
	v_mfma_f32_16x16x32_bf16 v[50:53], v[190:193], v[198:201], v[50:53]
	v_mfma_f32_16x16x32_bf16 v[38:41], v[176:179], v[214:217], v[38:41]
	v_mfma_f32_16x16x32_bf16 v[34:37], v[190:193], v[214:217], v[34:37]
	v_mfma_f32_16x16x32_bf16 v[22:25], v[176:179], v[222:225], v[22:25]
	v_mfma_f32_16x16x32_bf16 v[18:21], v[190:193], v[222:225], v[18:21]
	v_mfma_f32_16x16x32_bf16 v[6:9], v[176:179], v[230:233], v[6:9]
	v_mfma_f32_16x16x32_bf16 v[2:5], v[190:193], v[230:233], v[2:5]
	s_barrier
	s_setprio 0
	s_add_i32 s45, 0, 0x18000
	v_add_u32_e32 v0, s45, v181
	s_add_i32 s75, 0, 0x1c000
	ds_read_b128 v[130:133], v0
	ds_read_b128 v[134:137], v0 offset:1024
	ds_read_b128 v[138:141], v0 offset:2048
	ds_read_b128 v[142:145], v0 offset:3072
	v_add_u32_e32 v0, s75, v181
	ds_read_b128 v[172:175], v0
	ds_read_b128 v[176:179], v0 offset:1024
	ds_read_b128 v[186:189], v0 offset:2048
	ds_read_b128 v[190:193], v0 offset:3072
	s_add_u32 s34, s34, 0x40000
	s_addc_u32 s35, s35, 0
	s_mov_b32 m0, s48
	v_lshl_add_u64 v[240:241], s[34:35], 0, v[146:147]
	ds_read_b128 v[194:197], v185 offset:32768
	ds_read_b128 v[198:201], v185 offset:33792
	ds_read_b128 v[210:213], v185 offset:34816
	ds_read_b128 v[214:217], v185 offset:35840
	ds_read_b128 v[218:221], v185 offset:36864
	ds_read_b128 v[222:225], v185 offset:37888
	ds_read_b128 v[226:229], v185 offset:38912
	ds_read_b128 v[230:233], v185 offset:39936
	global_load_lds_dwordx4 v[240:241], off
	v_lshl_add_u64 v[240:241], s[34:35], 0, v[150:151]
	s_mov_b32 m0, s49
	s_nop 0
	global_load_lds_dwordx4 v[240:241], off
	s_waitcnt vmcnt(8)
	s_waitcnt lgkmcnt(0)
	s_barrier
	s_setprio 1
	v_mfma_f32_16x16x32_bf16 v[126:129], v[130:133], v[194:197], v[126:129]
	v_mfma_f32_16x16x32_bf16 v[122:125], v[138:141], v[194:197], v[122:125]
	v_mfma_f32_16x16x32_bf16 v[110:113], v[130:133], v[210:213], v[110:113]
	v_mfma_f32_16x16x32_bf16 v[106:109], v[138:141], v[210:213], v[106:109]
	v_mfma_f32_16x16x32_bf16 v[94:97], v[130:133], v[218:221], v[94:97]
	v_mfma_f32_16x16x32_bf16 v[90:93], v[138:141], v[218:221], v[90:93]
	v_mfma_f32_16x16x32_bf16 v[78:81], v[130:133], v[226:229], v[78:81]
	v_mfma_f32_16x16x32_bf16 v[74:77], v[138:141], v[226:229], v[74:77]
	v_mfma_f32_16x16x32_bf16 v[126:129], v[134:137], v[198:201], v[126:129]
	v_mfma_f32_16x16x32_bf16 v[122:125], v[142:145], v[198:201], v[122:125]
	v_mfma_f32_16x16x32_bf16 v[110:113], v[134:137], v[214:217], v[110:113]
	v_mfma_f32_16x16x32_bf16 v[106:109], v[142:145], v[214:217], v[106:109]
	v_mfma_f32_16x16x32_bf16 v[94:97], v[134:137], v[222:225], v[94:97]
	v_mfma_f32_16x16x32_bf16 v[90:93], v[142:145], v[222:225], v[90:93]
	v_mfma_f32_16x16x32_bf16 v[78:81], v[134:137], v[230:233], v[78:81]
	v_mfma_f32_16x16x32_bf16 v[74:77], v[142:145], v[230:233], v[74:77]
	s_setprio 0
	s_setprio 1
	v_mfma_f32_16x16x32_bf16 v[118:121], v[172:175], v[194:197], v[118:121]
	v_mfma_f32_16x16x32_bf16 v[114:117], v[186:189], v[194:197], v[114:117]
	v_mfma_f32_16x16x32_bf16 v[102:105], v[172:175], v[210:213], v[102:105]
	v_mfma_f32_16x16x32_bf16 v[98:101], v[186:189], v[210:213], v[98:101]
	v_mfma_f32_16x16x32_bf16 v[86:89], v[172:175], v[218:221], v[86:89]
	v_mfma_f32_16x16x32_bf16 v[82:85], v[186:189], v[218:221], v[82:85]
	v_mfma_f32_16x16x32_bf16 v[70:73], v[172:175], v[226:229], v[70:73]
	v_mfma_f32_16x16x32_bf16 v[66:69], v[186:189], v[226:229], v[66:69]
	v_mfma_f32_16x16x32_bf16 v[118:121], v[176:179], v[198:201], v[118:121]
	v_mfma_f32_16x16x32_bf16 v[114:117], v[190:193], v[198:201], v[114:117]
	v_mfma_f32_16x16x32_bf16 v[102:105], v[176:179], v[214:217], v[102:105]
	v_mfma_f32_16x16x32_bf16 v[98:101], v[190:193], v[214:217], v[98:101]
	v_mfma_f32_16x16x32_bf16 v[86:89], v[176:179], v[222:225], v[86:89]
	v_mfma_f32_16x16x32_bf16 v[82:85], v[190:193], v[222:225], v[82:85]
	v_mfma_f32_16x16x32_bf16 v[70:73], v[176:179], v[230:233], v[70:73]
	v_mfma_f32_16x16x32_bf16 v[66:69], v[190:193], v[230:233], v[66:69]
	s_barrier
; #define PG8_STAGE(bufoff, gbase, voff) do { _Pragma("unroll") for (int _i = 0; _i < 2; ++_i) \
;         __builtin_amdgcn_global_load_lds((const unsigned*)((const char*)(gbase) + (voff)[_i]), (PG8_LAS unsigned*)(lds + (bufoff) + ldsw + _i * 8192), 16, 0, 0); } while (0)
; #define PG8_LDA(dst, b, h) do { _Pragma("unroll") for (int m = 0; m < 4; ++m) _Pragma("unroll") for (int k = 0; k < 2; ++k) dst[m][k] = *(const PG8_LAS bf16x8*)(lds + PG8_SA(b, h) + aoff + m * 2048 + k * 1024); } while (0)
; #define PG8_BAR __builtin_amdgcn_s_barrier()
; template <class Epi, class Sched, bool ALIGN_EPI = false, bool SP2 = false>
; __device__ __forceinline__ void gemm_phase(PG8_LAS unsigned char* lds, const Gemm g, const Sched& S, const Epi& E, const int wave_s) {
;     ...
;             PG8_LDA(At, 1, 1); PG8_STAGE(PG8_SB(1, 0), b3, voffB); PG8_STAGE(PG8_SB(1, 1), b3 + hstep, voffB); PG8_STAGE(PG8_SA(1, 0), a3, voffA);
;             PG8_WAIT_V(8); PG8_WAIT_L(0); PG8_BAR; PG8_MMA(1, 0, At, B0); PG8_MMA(1, 1, At, B1); PG8_BAR; PG8_SCHED;
;             } else {
;             PG8_LDB(B0, 0, 0); PG8_SCHED; PG8_LDA(At, 0, 0); PG8_STAGE(PG8_SA(1, 1), a1 + hstep, voffA);
;             PG8_WAIT_L(8); PG8_BAR; PG8_WAIT_L(0); PG8_MMA(0, 0, At, B0); PG8_BAR; PG8_SCHED;
;             PG8_LDB(B1, 0, 1); PG8_STAGE(PG8_SB(0, 0), b2, voffB);
;             PG8_BAR; PG8_WAIT_L(0); PG8_MMA(0, 1, At, B1); PG8_BAR;
;             PG8_LDA(At, 0, 1); PG8_STAGE(PG8_SA(0, 0), a2, voffA);
;             PG8_BAR; PG8_WAIT_L(0); PG8_MMA(1, 0, At, B0); PG8_BAR; PG8_SCHED;
;             PG8_STAGE(PG8_SB(0, 1), b2 + hstep, voffB);
;             PG8_WAIT_V(6); PG8_BAR; PG8_MMA(1, 1, At, B1); PG8_BAR;
;             PG8_LDB(B0, 1, 0); PG8_SCHED; PG8_LDA(At, 1, 0); PG8_STAGE(PG8_SA(0, 1), a2 + hstep, voffA);
;             PG8_WAIT_L(8); PG8_BAR; PG8_WAIT_L(0); PG8_MMA(0, 0, At, B0); PG8_BAR; PG8_SCHED;
;             PG8_LDB(B1, 1, 1); PG8_STAGE(PG8_SB(1, 0), b3, voffB);
;             PG8_BAR; PG8_WAIT_L(0); PG8_MMA(0, 1, At, B1); PG8_BAR;
;             PG8_LDA(At, 1, 1); PG8_STAGE(PG8_SA(1, 0), a3, voffA);
;             PG8_BAR; PG8_WAIT_L(0); PG8_MMA(1, 0, At, B0); PG8_BAR; PG8_SCHED;
;             PG8_STAGE(PG8_SB(1, 1), b3 + hstep, voffB);
;             PG8_WAIT_V(6); PG8_BAR; PG8_MMA(1, 1, At, B1); PG8_BAR;
;             }
;         }
;         if constexpr (ALIGN_EPI) { if (wr == 0) PG8_BAR; }
	s_setprio 0
	s_add_i32 s34, s45, s44
	v_lshl_add_u64 v[202:203], v[202:203], 0, s[70:71]
	s_mov_b32 m0, s34
	ds_read_b128 v[194:197], v185 offset:49152
	ds_read_b128 v[198:201], v185 offset:50176
	ds_read_b128 v[210:213], v185 offset:51200
	ds_read_b128 v[214:217], v185 offset:52224
	ds_read_b128 v[218:221], v185 offset:53248
	ds_read_b128 v[222:225], v185 offset:54272
	ds_read_b128 v[226:229], v185 offset:55296
	ds_read_b128 v[230:233], v185 offset:56320
	global_load_lds_dwordx4 v[202:203], off
	s_add_i32 m0, s34, 0x2000
	s_add_u32 s30, s30, 0x40080
	v_lshl_add_u64 v[202:203], v[234:235], 0, s[70:71]
	s_addc_u32 s31, s31, 0
	s_add_i32 s34, s75, s44
	global_load_lds_dwordx4 v[202:203], off
	v_lshl_add_u64 v[202:203], s[30:31], 0, v[148:149]
	s_mov_b32 m0, s34
	s_nop 0
	global_load_lds_dwordx4 v[202:203], off
	v_lshl_add_u64 v[202:203], s[30:31], 0, v[152:153]
	s_add_i32 m0, s34, 0x2000
	s_nop 0
	global_load_lds_dwordx4 v[202:203], off
	v_lshl_add_u64 v[202:203], v[236:237], 0, s[70:71]
	s_mov_b32 m0, s88
	s_nop 0
	global_load_lds_dwordx4 v[202:203], off
	v_lshl_add_u64 v[202:203], v[238:239], 0, s[70:71]
	s_mov_b32 m0, s89
	s_nop 0
	global_load_lds_dwordx4 v[202:203], off
	s_waitcnt vmcnt(8)
	s_waitcnt lgkmcnt(0)
	s_barrier
	s_setprio 1
	v_mfma_f32_16x16x32_bf16 v[62:65], v[130:133], v[194:197], v[62:65]
	v_mfma_f32_16x16x32_bf16 v[58:61], v[138:141], v[194:197], v[58:61]
	v_mfma_f32_16x16x32_bf16 v[46:49], v[130:133], v[210:213], v[46:49]
	v_mfma_f32_16x16x32_bf16 v[42:45], v[138:141], v[210:213], v[42:45]
	v_mfma_f32_16x16x32_bf16 v[30:33], v[130:133], v[218:221], v[30:33]
	v_mfma_f32_16x16x32_bf16 v[26:29], v[138:141], v[218:221], v[26:29]
	v_mfma_f32_16x16x32_bf16 v[14:17], v[130:133], v[226:229], v[14:17]
	v_mfma_f32_16x16x32_bf16 v[10:13], v[138:141], v[226:229], v[10:13]
	v_mfma_f32_16x16x32_bf16 v[62:65], v[134:137], v[198:201], v[62:65]
	v_mfma_f32_16x16x32_bf16 v[58:61], v[142:145], v[198:201], v[58:61]
	v_mfma_f32_16x16x32_bf16 v[46:49], v[134:137], v[214:217], v[46:49]
	v_mfma_f32_16x16x32_bf16 v[42:45], v[142:145], v[214:217], v[42:45]
	v_mfma_f32_16x16x32_bf16 v[30:33], v[134:137], v[222:225], v[30:33]
	v_mfma_f32_16x16x32_bf16 v[26:29], v[142:145], v[222:225], v[26:29]
	v_mfma_f32_16x16x32_bf16 v[14:17], v[134:137], v[230:233], v[14:17]
	v_mfma_f32_16x16x32_bf16 v[10:13], v[142:145], v[230:233], v[10:13]
	s_setprio 0
	s_setprio 1
	v_mfma_f32_16x16x32_bf16 v[54:57], v[172:175], v[194:197], v[54:57]
	v_mfma_f32_16x16x32_bf16 v[50:53], v[186:189], v[194:197], v[50:53]
	v_mfma_f32_16x16x32_bf16 v[38:41], v[172:175], v[210:213], v[38:41]
	v_mfma_f32_16x16x32_bf16 v[34:37], v[186:189], v[210:213], v[34:37]
	v_mfma_f32_16x16x32_bf16 v[22:25], v[172:175], v[218:221], v[22:25]
	v_mfma_f32_16x16x32_bf16 v[18:21], v[186:189], v[218:221], v[18:21]
	v_mfma_f32_16x16x32_bf16 v[6:9], v[172:175], v[226:229], v[6:9]
	v_mfma_f32_16x16x32_bf16 v[2:5], v[186:189], v[226:229], v[2:5]
	v_mfma_f32_16x16x32_bf16 v[54:57], v[176:179], v[198:201], v[54:57]
	v_mfma_f32_16x16x32_bf16 v[50:53], v[190:193], v[198:201], v[50:53]
	v_mfma_f32_16x16x32_bf16 v[38:41], v[176:179], v[214:217], v[38:41]
	v_mfma_f32_16x16x32_bf16 v[34:37], v[190:193], v[214:217], v[34:37]
	v_mfma_f32_16x16x32_bf16 v[22:25], v[176:179], v[222:225], v[22:25]
	v_mfma_f32_16x16x32_bf16 v[18:21], v[190:193], v[222:225], v[18:21]
	v_mfma_f32_16x16x32_bf16 v[6:9], v[176:179], v[230:233], v[6:9]
	v_mfma_f32_16x16x32_bf16 v[2:5], v[190:193], v[230:233], v[2:5]
	s_barrier
	s_setprio 0
	s_add_i32 s68, s68, 2
	s_add_u32 s28, s28, 0x100
	s_addc_u32 s29, s29, 0
	s_add_u32 s64, s64, 0x100
	s_addc_u32 s65, s65, 0
	s_cmp_gt_u32 s68, 13
	s_cbranch_scc0 .LBB0_325
	s_and_b64 vcc, exec, s[14:15]
	s_cbranch_vccz .LBB0_328
	s_barrier

; #define PG8_STAGE(bufoff, gbase, voff) do { _Pragma("unroll") for (int _i = 0; _i < 2; ++_i) \
;         __builtin_amdgcn_global_load_lds((const unsigned*)((const char*)(gbase) + (voff)[_i]), (PG8_LAS unsigned*)(lds + (bufoff) + ldsw + _i * 8192), 16, 0, 0); } while (0)
; #define PG8_LDA(dst, b, h) do { _Pragma("unroll") for (int m = 0; m < 4; ++m) _Pragma("unroll") for (int k = 0; k < 2; ++k) dst[m][k] = *(const PG8_LAS bf16x8*)(lds + PG8_SA(b, h) + aoff + m * 2048 + k * 1024); } while (0)
; #define PG8_LDB(dst, b, h) do { _Pragma("unroll") for (int n = 0; n < 2; ++n) _Pragma("unroll") for (int k = 0; k < 2; ++k) dst[n][k] = *(const PG8_LAS bf16x8*)(lds + PG8_SB(b, h) + boff + n * 2048 + k * 1024); } while (0)
; #define PG8_MMA(ai, bj, At, Bt) do { __builtin_amdgcn_s_setprio(1); _Pragma("unroll") for (int m = 0; m < 4; ++m) _Pragma("unroll") for (int n = 0; n < 2; ++n) _Pragma("unroll") for (int k = 0; k < 2; ++k) \
;         acc[ai][bj][m][n] = __builtin_amdgcn_mfma_f32_16x16x32_bf16(Bt[n][k], At[m][k], acc[ai][bj][m][n], 0, 0, 0); __builtin_amdgcn_s_setprio(0); } while (0)
; #define PG8_WAIT_V(n) asm volatile("s_waitcnt vmcnt(" #n ")" ::: "memory")
; #define PG8_WAIT_L(n) asm volatile("s_waitcnt lgkmcnt(" #n ")" ::: "memory")
; template <class Epi, class Sched, bool ALIGN_EPI = false, bool SP2 = false>
; __device__ __forceinline__ void gemm_phase(PG8_LAS unsigned char* lds, const Gemm g, const Sched& S, const Epi& E, const int wave_s) {
;     ...
;             const bool last = (t == nt - 2);
;             const char* a1 = cA + (size_t)(t + 1) * kstep;
;             const char* a2 = last ? nA : cA + (size_t)(t + 2) * kstep; const char* b2 = last ? nB : cB + (size_t)(t + 2) * kstep;
;             const char* a3 = a2 + kstep; const char* b3 = b2 + kstep;
;             if (last && has_next) S.a_ready(nxt);
;             if constexpr (SP2) {
;             PG8_LDB(B0, 0, 0); PG8_LDB(B1, 0, 1); PG8_SCHED; PG8_LDA(At, 0, 0); PG8_STAGE(PG8_SA(1, 1), a1 + hstep, voffA);
;             PG8_WAIT_V(8); PG8_WAIT_L(0); PG8_BAR; PG8_MMA(0, 0, At, B0); PG8_MMA(0, 1, At, B1); PG8_BAR; PG8_SCHED;
;             PG8_LDA(At, 0, 1); PG8_STAGE(PG8_SB(0, 0), b2, voffB); PG8_STAGE(PG8_SB(0, 1), b2 + hstep, voffB); PG8_STAGE(PG8_SA(0, 0), a2, voffA);
;             PG8_WAIT_V(8); PG8_WAIT_L(0); PG8_BAR; PG8_MMA(1, 0, At, B0); PG8_MMA(1, 1, At, B1); PG8_BAR; PG8_SCHED;
.LBB0_658:
	s_add_u32 s36, s34, 0xfffc0080
	s_addc_u32 s37, s35, -1
	s_add_i32 s45, 0, 0x10000
	s_cmp_eq_u32 s50, 12
	s_cselect_b32 s41, s27, s37
	s_cselect_b32 s40, s55, s36
	v_add_u32_e32 v152, s45, v195
	s_cselect_b32 s37, s25, vcc_hi
	s_cselect_b32 s36, s97, vcc_lo
	s_add_i32 s75, 0, 0x14000
	ds_read_b128 v[94:97], v152
	ds_read_b128 v[98:101], v152 offset:1024
	ds_read_b128 v[148:151], v152 offset:2048
	ds_read_b128 v[162:165], v152 offset:3072
	v_add_u32_e32 v152, s75, v195
	ds_read_b128 v[166:169], v152
	ds_read_b128 v[170:173], v152 offset:1024
	ds_read_b128 v[174:177], v152 offset:2048
	ds_read_b128 v[178:181], v152 offset:3072
	v_lshl_add_u64 v[152:153], s[34:35], 0, v[144:145]
	s_add_i32 m0, s88, 0xc000
	ds_read_b128 v[182:185], v198
	ds_read_b128 v[186:189], v198 offset:1024
	ds_read_b128 v[190:193], v198 offset:2048
	ds_read_b128 v[200:203], v198 offset:3072
	ds_read_b128 v[210:213], v198 offset:4096
	ds_read_b128 v[214:217], v198 offset:5120
	ds_read_b128 v[218:221], v198 offset:6144
	ds_read_b128 v[222:225], v198 offset:7168
	global_load_lds_dwordx4 v[152:153], off
	v_lshl_add_u64 v[152:153], s[34:35], 0, v[146:147]
	s_add_i32 m0, s88, 0xe000
	s_nop 0
	global_load_lds_dwordx4 v[152:153], off
	s_waitcnt vmcnt(8)
	s_waitcnt lgkmcnt(0)
	s_barrier
	s_setprio 1
	v_mfma_f32_16x16x32_bf16 v[134:137], v[94:97], v[182:185], v[134:137]
	v_mfma_f32_16x16x32_bf16 v[130:133], v[148:151], v[182:185], v[130:133]
	v_mfma_f32_16x16x32_bf16 v[126:129], v[94:97], v[190:193], v[126:129]
	v_mfma_f32_16x16x32_bf16 v[122:125], v[148:151], v[190:193], v[122:125]
	v_mfma_f32_16x16x32_bf16 v[118:121], v[94:97], v[210:213], v[118:121]
	v_mfma_f32_16x16x32_bf16 v[114:117], v[148:151], v[210:213], v[114:117]
	v_mfma_f32_16x16x32_bf16 v[110:113], v[94:97], v[218:221], v[110:113]
	v_mfma_f32_16x16x32_bf16 v[106:109], v[148:151], v[218:221], v[106:109]
	v_mfma_f32_16x16x32_bf16 v[134:137], v[98:101], v[186:189], v[134:137]
	v_mfma_f32_16x16x32_bf16 v[130:133], v[162:165], v[186:189], v[130:133]
	v_mfma_f32_16x16x32_bf16 v[126:129], v[98:101], v[200:203], v[126:129]
	v_mfma_f32_16x16x32_bf16 v[122:125], v[162:165], v[200:203], v[122:125]
	v_mfma_f32_16x16x32_bf16 v[118:121], v[98:101], v[214:217], v[118:121]
	v_mfma_f32_16x16x32_bf16 v[114:117], v[162:165], v[214:217], v[114:117]
	v_mfma_f32_16x16x32_bf16 v[110:113], v[98:101], v[222:225], v[110:113]
	v_mfma_f32_16x16x32_bf16 v[106:109], v[162:165], v[222:225], v[106:109]
	s_setprio 0
	s_setprio 1
	v_mfma_f32_16x16x32_bf16 v[58:61], v[166:169], v[182:185], v[58:61]
	v_mfma_f32_16x16x32_bf16 v[62:65], v[174:177], v[182:185], v[62:65]
	v_mfma_f32_16x16x32_bf16 v[54:57], v[166:169], v[190:193], v[54:57]
	v_mfma_f32_16x16x32_bf16 v[50:53], v[174:177], v[190:193], v[50:53]
	v_mfma_f32_16x16x32_bf16 v[46:49], v[166:169], v[210:213], v[46:49]
	v_mfma_f32_16x16x32_bf16 v[42:45], v[174:177], v[210:213], v[42:45]
	v_mfma_f32_16x16x32_bf16 v[38:41], v[166:169], v[218:221], v[38:41]
	v_mfma_f32_16x16x32_bf16 v[34:37], v[174:177], v[218:221], v[34:37]
	v_mfma_f32_16x16x32_bf16 v[58:61], v[170:173], v[186:189], v[58:61]
	v_mfma_f32_16x16x32_bf16 v[62:65], v[178:181], v[186:189], v[62:65]
	v_mfma_f32_16x16x32_bf16 v[54:57], v[170:173], v[200:203], v[54:57]
	v_mfma_f32_16x16x32_bf16 v[50:53], v[178:181], v[200:203], v[50:53]
	v_mfma_f32_16x16x32_bf16 v[46:49], v[170:173], v[214:217], v[46:49]
	v_mfma_f32_16x16x32_bf16 v[42:45], v[178:181], v[214:217], v[42:45]
	v_mfma_f32_16x16x32_bf16 v[38:41], v[170:173], v[222:225], v[38:41]
	v_mfma_f32_16x16x32_bf16 v[34:37], v[178:181], v[222:225], v[34:37]
	s_barrier
	s_setprio 0
	s_add_i32 s45, s45, s68
	v_lshl_add_u64 v[152:153], s[36:37], 0, v[0:1]
	s_mov_b32 m0, s45
	ds_read_b128 v[182:185], v198 offset:16384
	ds_read_b128 v[186:189], v198 offset:17408
	ds_read_b128 v[190:193], v198 offset:18432
	ds_read_b128 v[200:203], v198 offset:19456
	ds_read_b128 v[210:213], v198 offset:20480
	ds_read_b128 v[214:217], v198 offset:21504
	ds_read_b128 v[218:221], v198 offset:22528
	ds_read_b128 v[222:225], v198 offset:23552
	global_load_lds_dwordx4 v[152:153], off
	s_add_i32 m0, s45, 0x2000
	s_add_u32 s80, s36, 0x40000
	v_lshl_add_u64 v[226:227], s[36:37], 0, v[138:139]
	s_addc_u32 s81, s37, 0
	s_add_i32 s45, s75, s68
	global_load_lds_dwordx4 v[226:227], off
	v_lshl_add_u64 v[228:229], s[80:81], 0, v[0:1]
	s_mov_b32 m0, s45
	v_lshl_add_u64 v[230:231], s[40:41], 0, v[140:141]
	global_load_lds_dwordx4 v[228:229], off
	v_lshl_add_u64 v[228:229], s[80:81], 0, v[138:139]
	s_add_i32 m0, s45, 0x2000
	s_nop 0
	global_load_lds_dwordx4 v[228:229], off
	v_lshl_add_u64 v[228:229], s[40:41], 0, v[142:143]
	s_mov_b32 m0, s88
	s_nop 0
	global_load_lds_dwordx4 v[228:229], off
	s_mov_b32 m0, s89
	s_nop 0
	global_load_lds_dwordx4 v[230:231], off
	s_waitcnt vmcnt(8)
	s_waitcnt lgkmcnt(0)
	s_barrier
; #define PG8_STAGE(bufoff, gbase, voff) do { _Pragma("unroll") for (int _i = 0; _i < 2; ++_i) \
;         __builtin_amdgcn_global_load_lds((const unsigned*)((const char*)(gbase) + (voff)[_i]), (PG8_LAS unsigned*)(lds + (bufoff) + ldsw + _i * 8192), 16, 0, 0); } while (0)
; #define PG8_LDA(dst, b, h) do { _Pragma("unroll") for (int m = 0; m < 4; ++m) _Pragma("unroll") for (int k = 0; k < 2; ++k) dst[m][k] = *(const PG8_LAS bf16x8*)(lds + PG8_SA(b, h) + aoff + m * 2048 + k * 1024); } while (0)
; #define PG8_LDB(dst, b, h) do { _Pragma("unroll") for (int n = 0; n < 2; ++n) _Pragma("unroll") for (int k = 0; k < 2; ++k) dst[n][k] = *(const PG8_LAS bf16x8*)(lds + PG8_SB(b, h) + boff + n * 2048 + k * 1024); } while (0)
; #define PG8_MMA(ai, bj, At, Bt) do { __builtin_amdgcn_s_setprio(1); _Pragma("unroll") for (int m = 0; m < 4; ++m) _Pragma("unroll") for (int n = 0; n < 2; ++n) _Pragma("unroll") for (int k = 0; k < 2; ++k) \
;         acc[ai][bj][m][n] = __builtin_amdgcn_mfma_f32_16x16x32_bf16(Bt[n][k], At[m][k], acc[ai][bj][m][n], 0, 0, 0); __builtin_amdgcn_s_setprio(0); } while (0)
; #define PG8_WAIT_V(n) asm volatile("s_waitcnt vmcnt(" #n ")" ::: "memory")
; #define PG8_WAIT_L(n) asm volatile("s_waitcnt lgkmcnt(" #n ")" ::: "memory")
; #define PG8_BAR __builtin_amdgcn_s_barrier()
; #define PG8_SCHED __builtin_amdgcn_sched_barrier(0)
; template <class Epi, class Sched, bool ALIGN_EPI = false, bool SP2 = false>
; __device__ __forceinline__ void gemm_phase(PG8_LAS unsigned char* lds, const Gemm g, const Sched& S, const Epi& E, const int wave_s) {
;     ...
;             PG8_WAIT_V(8); PG8_WAIT_L(0); PG8_BAR; PG8_MMA(1, 0, At, B0); PG8_MMA(1, 1, At, B1); PG8_BAR; PG8_SCHED;
;             PG8_LDB(B0, 1, 0); PG8_LDB(B1, 1, 1); PG8_SCHED; PG8_LDA(At, 1, 0); PG8_STAGE(PG8_SA(0, 1), a2 + hstep, voffA);
;             PG8_WAIT_V(8); PG8_WAIT_L(0); PG8_BAR; PG8_MMA(0, 0, At, B0); PG8_MMA(0, 1, At, B1); PG8_BAR; PG8_SCHED;
	s_setprio 1
	v_mfma_f32_16x16x32_bf16 v[102:105], v[94:97], v[182:185], v[102:105]
	v_mfma_f32_16x16x32_bf16 v[90:93], v[148:151], v[182:185], v[90:93]
	v_mfma_f32_16x16x32_bf16 v[86:89], v[94:97], v[190:193], v[86:89]
	v_mfma_f32_16x16x32_bf16 v[82:85], v[148:151], v[190:193], v[82:85]
	v_mfma_f32_16x16x32_bf16 v[78:81], v[94:97], v[210:213], v[78:81]
	v_mfma_f32_16x16x32_bf16 v[74:77], v[148:151], v[210:213], v[74:77]
	v_mfma_f32_16x16x32_bf16 v[70:73], v[94:97], v[218:221], v[70:73]
	v_mfma_f32_16x16x32_bf16 v[66:69], v[148:151], v[218:221], v[66:69]
	v_mfma_f32_16x16x32_bf16 v[102:105], v[98:101], v[186:189], v[102:105]
	v_mfma_f32_16x16x32_bf16 v[90:93], v[162:165], v[186:189], v[90:93]
	v_mfma_f32_16x16x32_bf16 v[86:89], v[98:101], v[200:203], v[86:89]
	v_mfma_f32_16x16x32_bf16 v[82:85], v[162:165], v[200:203], v[82:85]
	v_mfma_f32_16x16x32_bf16 v[78:81], v[98:101], v[214:217], v[78:81]
	v_mfma_f32_16x16x32_bf16 v[74:77], v[162:165], v[214:217], v[74:77]
	v_mfma_f32_16x16x32_bf16 v[70:73], v[98:101], v[222:225], v[70:73]
	v_mfma_f32_16x16x32_bf16 v[66:69], v[162:165], v[222:225], v[66:69]
	s_setprio 0
	s_setprio 1
	v_mfma_f32_16x16x32_bf16 v[30:33], v[166:169], v[182:185], v[30:33]
	v_mfma_f32_16x16x32_bf16 v[26:29], v[174:177], v[182:185], v[26:29]
	v_mfma_f32_16x16x32_bf16 v[22:25], v[166:169], v[190:193], v[22:25]
	v_mfma_f32_16x16x32_bf16 v[18:21], v[174:177], v[190:193], v[18:21]
	v_mfma_f32_16x16x32_bf16 v[14:17], v[166:169], v[210:213], v[14:17]
	v_mfma_f32_16x16x32_bf16 v[10:13], v[174:177], v[210:213], v[10:13]
	v_mfma_f32_16x16x32_bf16 v[6:9], v[166:169], v[218:221], v[6:9]
	v_mfma_f32_16x16x32_bf16 v[2:5], v[174:177], v[218:221], v[2:5]
	v_mfma_f32_16x16x32_bf16 v[30:33], v[170:173], v[186:189], v[30:33]
	v_mfma_f32_16x16x32_bf16 v[26:29], v[178:181], v[186:189], v[26:29]
	v_mfma_f32_16x16x32_bf16 v[22:25], v[170:173], v[200:203], v[22:25]
	v_mfma_f32_16x16x32_bf16 v[18:21], v[178:181], v[200:203], v[18:21]
	v_mfma_f32_16x16x32_bf16 v[14:17], v[170:173], v[214:217], v[14:17]
	v_mfma_f32_16x16x32_bf16 v[10:13], v[178:181], v[214:217], v[10:13]
	v_mfma_f32_16x16x32_bf16 v[6:9], v[170:173], v[222:225], v[6:9]
	v_mfma_f32_16x16x32_bf16 v[2:5], v[178:181], v[222:225], v[2:5]
	s_barrier
	s_setprio 0
	s_add_i32 s45, 0, 0x18000
	s_add_i32 s75, 0, 0x1c000
	v_add_u32_e32 v162, s45, v195
	v_add_u32_e32 v178, s75, v195
	ds_read_b128 v[94:97], v162
	ds_read_b128 v[98:101], v162 offset:1024
	ds_read_b128 v[148:151], v162 offset:2048
	ds_read_b128 v[162:165], v162 offset:3072
	ds_read_b128 v[166:169], v178
	ds_read_b128 v[170:173], v178 offset:1024
	ds_read_b128 v[174:177], v178 offset:2048
	ds_read_b128 v[178:181], v178 offset:3072
	s_add_u32 s40, s40, 0x40000
	s_addc_u32 s41, s41, 0
	s_mov_b32 m0, s38
	v_lshl_add_u64 v[232:233], s[40:41], 0, v[142:143]
	ds_read_b128 v[182:185], v198 offset:32768
	ds_read_b128 v[186:189], v198 offset:33792
	ds_read_b128 v[190:193], v198 offset:34816
	ds_read_b128 v[200:203], v198 offset:35840
	ds_read_b128 v[210:213], v198 offset:36864
	ds_read_b128 v[214:217], v198 offset:37888
	ds_read_b128 v[218:221], v198 offset:38912
	ds_read_b128 v[222:225], v198 offset:39936
	global_load_lds_dwordx4 v[232:233], off
	v_lshl_add_u64 v[232:233], s[40:41], 0, v[140:141]
	s_mov_b32 m0, s39
	s_nop 0
	global_load_lds_dwordx4 v[232:233], off
	s_waitcnt vmcnt(8)
	s_waitcnt lgkmcnt(0)
	s_barrier
	s_setprio 1
	v_mfma_f32_16x16x32_bf16 v[134:137], v[94:97], v[182:185], v[134:137]
	v_mfma_f32_16x16x32_bf16 v[130:133], v[148:151], v[182:185], v[130:133]
	v_mfma_f32_16x16x32_bf16 v[126:129], v[94:97], v[190:193], v[126:129]
	v_mfma_f32_16x16x32_bf16 v[122:125], v[148:151], v[190:193], v[122:125]
	v_mfma_f32_16x16x32_bf16 v[118:121], v[94:97], v[210:213], v[118:121]
	v_mfma_f32_16x16x32_bf16 v[114:117], v[148:151], v[210:213], v[114:117]
	v_mfma_f32_16x16x32_bf16 v[110:113], v[94:97], v[218:221], v[110:113]
	v_mfma_f32_16x16x32_bf16 v[106:109], v[148:151], v[218:221], v[106:109]
	v_mfma_f32_16x16x32_bf16 v[134:137], v[98:101], v[186:189], v[134:137]
	v_mfma_f32_16x16x32_bf16 v[130:133], v[162:165], v[186:189], v[130:133]
	v_mfma_f32_16x16x32_bf16 v[126:129], v[98:101], v[200:203], v[126:129]
	v_mfma_f32_16x16x32_bf16 v[122:125], v[162:165], v[200:203], v[122:125]
	v_mfma_f32_16x16x32_bf16 v[118:121], v[98:101], v[214:217], v[118:121]
	v_mfma_f32_16x16x32_bf16 v[114:117], v[162:165], v[214:217], v[114:117]
	v_mfma_f32_16x16x32_bf16 v[110:113], v[98:101], v[222:225], v[110:113]
	v_mfma_f32_16x16x32_bf16 v[106:109], v[162:165], v[222:225], v[106:109]
	s_setprio 0
	s_setprio 1
	v_mfma_f32_16x16x32_bf16 v[58:61], v[166:169], v[182:185], v[58:61]
	v_mfma_f32_16x16x32_bf16 v[62:65], v[174:177], v[182:185], v[62:65]
	v_mfma_f32_16x16x32_bf16 v[54:57], v[166:169], v[190:193], v[54:57]
	v_mfma_f32_16x16x32_bf16 v[50:53], v[174:177], v[190:193], v[50:53]
	v_mfma_f32_16x16x32_bf16 v[46:49], v[166:169], v[210:213], v[46:49]
	v_mfma_f32_16x16x32_bf16 v[42:45], v[174:177], v[210:213], v[42:45]
	v_mfma_f32_16x16x32_bf16 v[38:41], v[166:169], v[218:221], v[38:41]
	v_mfma_f32_16x16x32_bf16 v[34:37], v[174:177], v[218:221], v[34:37]
	v_mfma_f32_16x16x32_bf16 v[58:61], v[170:173], v[186:189], v[58:61]
	v_mfma_f32_16x16x32_bf16 v[62:65], v[178:181], v[186:189], v[62:65]
	v_mfma_f32_16x16x32_bf16 v[54:57], v[170:173], v[200:203], v[54:57]
	v_mfma_f32_16x16x32_bf16 v[50:53], v[178:181], v[200:203], v[50:53]
	v_mfma_f32_16x16x32_bf16 v[46:49], v[170:173], v[214:217], v[46:49]
	v_mfma_f32_16x16x32_bf16 v[42:45], v[178:181], v[214:217], v[42:45]
	v_mfma_f32_16x16x32_bf16 v[38:41], v[170:173], v[222:225], v[38:41]
	v_mfma_f32_16x16x32_bf16 v[34:37], v[178:181], v[222:225], v[34:37]
	s_barrier
; #define PG8_STAGE(bufoff, gbase, voff) do { _Pragma("unroll") for (int _i = 0; _i < 2; ++_i) \
;         __builtin_amdgcn_global_load_lds((const unsigned*)((const char*)(gbase) + (voff)[_i]), (PG8_LAS unsigned*)(lds + (bufoff) + ldsw + _i * 8192), 16, 0, 0); } while (0)
; #define PG8_LDA(dst, b, h) do { _Pragma("unroll") for (int m = 0; m < 4; ++m) _Pragma("unroll") for (int k = 0; k < 2; ++k) dst[m][k] = *(const PG8_LAS bf16x8*)(lds + PG8_SA(b, h) + aoff + m * 2048 + k * 1024); } while (0)
; #define PG8_BAR __builtin_amdgcn_s_barrier()
; template <class Epi, class Sched, bool ALIGN_EPI = false, bool SP2 = false>
; __device__ __forceinline__ void gemm_phase(PG8_LAS unsigned char* lds, const Gemm g, const Sched& S, const Epi& E, const int wave_s) {
;     ...
;             PG8_LDA(At, 1, 1); PG8_STAGE(PG8_SB(1, 0), b3, voffB); PG8_STAGE(PG8_SB(1, 1), b3 + hstep, voffB); PG8_STAGE(PG8_SA(1, 0), a3, voffA);
;             PG8_WAIT_V(8); PG8_WAIT_L(0); PG8_BAR; PG8_MMA(1, 0, At, B0); PG8_MMA(1, 1, At, B1); PG8_BAR; PG8_SCHED;
;             } else {
;             PG8_LDB(B0, 0, 0); PG8_SCHED; PG8_LDA(At, 0, 0); PG8_STAGE(PG8_SA(1, 1), a1 + hstep, voffA);
;             PG8_WAIT_L(8); PG8_BAR; PG8_WAIT_L(0); PG8_MMA(0, 0, At, B0); PG8_BAR; PG8_SCHED;
;             PG8_LDB(B1, 0, 1); PG8_STAGE(PG8_SB(0, 0), b2, voffB);
;             PG8_BAR; PG8_WAIT_L(0); PG8_MMA(0, 1, At, B1); PG8_BAR;
;             PG8_LDA(At, 0, 1); PG8_STAGE(PG8_SA(0, 0), a2, voffA);
;             PG8_BAR; PG8_WAIT_L(0); PG8_MMA(1, 0, At, B0); PG8_BAR; PG8_SCHED;
;             PG8_STAGE(PG8_SB(0, 1), b2 + hstep, voffB);
;             PG8_WAIT_V(6); PG8_BAR; PG8_MMA(1, 1, At, B1); PG8_BAR;
;             PG8_LDB(B0, 1, 0); PG8_SCHED; PG8_LDA(At, 1, 0); PG8_STAGE(PG8_SA(0, 1), a2 + hstep, voffA);
;             PG8_WAIT_L(8); PG8_BAR; PG8_WAIT_L(0); PG8_MMA(0, 0, At, B0); PG8_BAR; PG8_SCHED;
;             PG8_LDB(B1, 1, 1); PG8_STAGE(PG8_SB(1, 0), b3, voffB);
;             PG8_BAR; PG8_WAIT_L(0); PG8_MMA(0, 1, At, B1); PG8_BAR;
;             PG8_LDA(At, 1, 1); PG8_STAGE(PG8_SA(1, 0), a3, voffA);
;             PG8_BAR; PG8_WAIT_L(0); PG8_MMA(1, 0, At, B0); PG8_BAR; PG8_SCHED;
;             PG8_STAGE(PG8_SB(1, 1), b3 + hstep, voffB);
;             PG8_WAIT_V(6); PG8_BAR; PG8_MMA(1, 1, At, B1); PG8_BAR;
;             }
;         }
;         if constexpr (ALIGN_EPI) { if (wr == 0) PG8_BAR; }
	s_setprio 0
	s_add_i32 s40, s45, s68
	v_lshl_add_u64 v[152:153], v[152:153], 0, s[70:71]
	s_mov_b32 m0, s40
	ds_read_b128 v[182:185], v198 offset:49152
	ds_read_b128 v[186:189], v198 offset:50176
	ds_read_b128 v[190:193], v198 offset:51200
	ds_read_b128 v[200:203], v198 offset:52224
	ds_read_b128 v[210:213], v198 offset:53248
	ds_read_b128 v[214:217], v198 offset:54272
	ds_read_b128 v[218:221], v198 offset:55296
	ds_read_b128 v[222:225], v198 offset:56320
	global_load_lds_dwordx4 v[152:153], off
	s_add_i32 m0, s40, 0x2000
	s_add_u32 s36, s36, 0x40080
	v_lshl_add_u64 v[152:153], v[226:227], 0, s[70:71]
	s_addc_u32 s37, s37, 0
	s_add_i32 s40, s75, s68
	global_load_lds_dwordx4 v[152:153], off
	v_lshl_add_u64 v[152:153], s[36:37], 0, v[0:1]
	s_mov_b32 m0, s40
	s_nop 0
	global_load_lds_dwordx4 v[152:153], off
	v_lshl_add_u64 v[152:153], s[36:37], 0, v[138:139]
	s_add_i32 m0, s40, 0x2000
	s_nop 0
	global_load_lds_dwordx4 v[152:153], off
	v_lshl_add_u64 v[152:153], v[228:229], 0, s[70:71]
	s_mov_b32 m0, s44
	s_nop 0
	global_load_lds_dwordx4 v[152:153], off
	v_lshl_add_u64 v[152:153], v[230:231], 0, s[70:71]
	s_mov_b32 m0, s54
	s_nop 0
	global_load_lds_dwordx4 v[152:153], off
	s_waitcnt vmcnt(8)
	s_waitcnt lgkmcnt(0)
	s_barrier
	s_setprio 1
	v_mfma_f32_16x16x32_bf16 v[102:105], v[94:97], v[182:185], v[102:105]
	v_mfma_f32_16x16x32_bf16 v[90:93], v[148:151], v[182:185], v[90:93]
	v_mfma_f32_16x16x32_bf16 v[86:89], v[94:97], v[190:193], v[86:89]
	v_mfma_f32_16x16x32_bf16 v[82:85], v[148:151], v[190:193], v[82:85]
	v_mfma_f32_16x16x32_bf16 v[78:81], v[94:97], v[210:213], v[78:81]
	v_mfma_f32_16x16x32_bf16 v[74:77], v[148:151], v[210:213], v[74:77]
	v_mfma_f32_16x16x32_bf16 v[70:73], v[94:97], v[218:221], v[70:73]
	v_mfma_f32_16x16x32_bf16 v[66:69], v[148:151], v[218:221], v[66:69]
	v_mfma_f32_16x16x32_bf16 v[102:105], v[98:101], v[186:189], v[102:105]
	v_mfma_f32_16x16x32_bf16 v[90:93], v[162:165], v[186:189], v[90:93]
	v_mfma_f32_16x16x32_bf16 v[86:89], v[98:101], v[200:203], v[86:89]
	v_mfma_f32_16x16x32_bf16 v[82:85], v[162:165], v[200:203], v[82:85]
	v_mfma_f32_16x16x32_bf16 v[78:81], v[98:101], v[214:217], v[78:81]
	v_mfma_f32_16x16x32_bf16 v[74:77], v[162:165], v[214:217], v[74:77]
	v_mfma_f32_16x16x32_bf16 v[70:73], v[98:101], v[222:225], v[70:73]
	v_mfma_f32_16x16x32_bf16 v[66:69], v[162:165], v[222:225], v[66:69]
	s_setprio 0
	s_setprio 1
	v_mfma_f32_16x16x32_bf16 v[30:33], v[166:169], v[182:185], v[30:33]
	v_mfma_f32_16x16x32_bf16 v[26:29], v[174:177], v[182:185], v[26:29]
	v_mfma_f32_16x16x32_bf16 v[22:25], v[166:169], v[190:193], v[22:25]
	v_mfma_f32_16x16x32_bf16 v[18:21], v[174:177], v[190:193], v[18:21]
	v_mfma_f32_16x16x32_bf16 v[14:17], v[166:169], v[210:213], v[14:17]
	v_mfma_f32_16x16x32_bf16 v[10:13], v[174:177], v[210:213], v[10:13]
	v_mfma_f32_16x16x32_bf16 v[6:9], v[166:169], v[218:221], v[6:9]
	v_mfma_f32_16x16x32_bf16 v[2:5], v[174:177], v[218:221], v[2:5]
	v_mfma_f32_16x16x32_bf16 v[30:33], v[170:173], v[186:189], v[30:33]
	v_mfma_f32_16x16x32_bf16 v[26:29], v[178:181], v[186:189], v[26:29]
	v_mfma_f32_16x16x32_bf16 v[22:25], v[170:173], v[200:203], v[22:25]
	v_mfma_f32_16x16x32_bf16 v[18:21], v[178:181], v[200:203], v[18:21]
	v_mfma_f32_16x16x32_bf16 v[14:17], v[170:173], v[214:217], v[14:17]
	v_mfma_f32_16x16x32_bf16 v[10:13], v[178:181], v[214:217], v[10:13]
	v_mfma_f32_16x16x32_bf16 v[6:9], v[170:173], v[222:225], v[6:9]
	v_mfma_f32_16x16x32_bf16 v[2:5], v[178:181], v[222:225], v[2:5]
	s_barrier
	s_setprio 0
	s_add_i32 s50, s50, 2
	s_add_u32 s34, s34, 0x100
	s_addc_u32 s35, s35, 0
	s_add_u32 vcc_lo, vcc_lo, 0x100
	s_addc_u32 vcc_hi, vcc_hi, 0
	s_cmp_gt_u32 s50, 13
	s_cbranch_scc0 .LBB0_658
	s_and_b64 vcc, exec, s[22:23]
	s_cbranch_vccz .LBB0_661
	s_barrier

; #define PG8_STAGE(bufoff, gbase, voff) do { _Pragma("unroll") for (int _i = 0; _i < 2; ++_i) \
;         __builtin_amdgcn_global_load_lds((const unsigned*)((const char*)(gbase) + (voff)[_i]), (PG8_LAS unsigned*)(lds + (bufoff) + ldsw + _i * 8192), 16, 0, 0); } while (0)
; #define PG8_LDA(dst, b, h) do { _Pragma("unroll") for (int m = 0; m < 4; ++m) _Pragma("unroll") for (int k = 0; k < 2; ++k) dst[m][k] = *(const PG8_LAS bf16x8*)(lds + PG8_SA(b, h) + aoff + m * 2048 + k * 1024); } while (0)
; #define PG8_LDB(dst, b, h) do { _Pragma("unroll") for (int n = 0; n < 2; ++n) _Pragma("unroll") for (int k = 0; k < 2; ++k) dst[n][k] = *(const PG8_LAS bf16x8*)(lds + PG8_SB(b, h) + boff + n * 2048 + k * 1024); } while (0)
; #define PG8_MMA(ai, bj, At, Bt) do { __builtin_amdgcn_s_setprio(1); _Pragma("unroll") for (int m = 0; m < 4; ++m) _Pragma("unroll") for (int n = 0; n < 2; ++n) _Pragma("unroll") for (int k = 0; k < 2; ++k) \
;         acc[ai][bj][m][n] = __builtin_amdgcn_mfma_f32_16x16x32_bf16(Bt[n][k], At[m][k], acc[ai][bj][m][n], 0, 0, 0); __builtin_amdgcn_s_setprio(0); } while (0)
; #define PG8_WAIT_V(n) asm volatile("s_waitcnt vmcnt(" #n ")" ::: "memory")
; #define PG8_WAIT_L(n) asm volatile("s_waitcnt lgkmcnt(" #n ")" ::: "memory")
; template <class Epi, class Sched, bool ALIGN_EPI = false, bool SP2 = false>
; __device__ __forceinline__ void gemm_phase(PG8_LAS unsigned char* lds, const Gemm g, const Sched& S, const Epi& E, const int wave_s) {
;     ...
;             const bool last = (t == nt - 2);
;             const char* a1 = cA + (size_t)(t + 1) * kstep;
;             const char* a2 = last ? nA : cA + (size_t)(t + 2) * kstep; const char* b2 = last ? nB : cB + (size_t)(t + 2) * kstep;
;             const char* a3 = a2 + kstep; const char* b3 = b2 + kstep;
;             if (last && has_next) S.a_ready(nxt);
;             if constexpr (SP2) {
;             PG8_LDB(B0, 0, 0); PG8_LDB(B1, 0, 1); PG8_SCHED; PG8_LDA(At, 0, 0); PG8_STAGE(PG8_SA(1, 1), a1 + hstep, voffA);
;             PG8_WAIT_V(8); PG8_WAIT_L(0); PG8_BAR; PG8_MMA(0, 0, At, B0); PG8_MMA(0, 1, At, B1); PG8_BAR; PG8_SCHED;
;             PG8_LDA(At, 0, 1); PG8_STAGE(PG8_SB(0, 0), b2, voffB); PG8_STAGE(PG8_SB(0, 1), b2 + hstep, voffB); PG8_STAGE(PG8_SA(0, 0), a2, voffA);
;             PG8_WAIT_V(8); PG8_WAIT_L(0); PG8_BAR; PG8_MMA(1, 0, At, B0); PG8_MMA(1, 1, At, B1); PG8_BAR; PG8_SCHED;
.LBB0_734:
	s_add_u32 s26, s24, 0xfffc0080
	s_addc_u32 s27, s25, -1
	s_add_i32 s45, 0, 0x10000
	s_cmp_eq_u32 s50, 12
	s_cselect_b32 s29, s19, s27
	s_cselect_b32 s28, s54, s26
	s_cselect_b32 s27, s17, s59
	s_cselect_b32 s26, s55, s58
	s_add_i32 s68, 0, 0x14000
	v_add_u32_e32 v50, s45, v171
	v_add_u32_e32 v152, s68, v171
	ds_read_b128 v[26:29], v50
	ds_read_b128 v[30:33], v50 offset:1024
	ds_read_b128 v[46:49], v50 offset:2048
	ds_read_b128 v[50:53], v50 offset:3072
	ds_read_b128 v[162:165], v152
	ds_read_b128 v[166:169], v152 offset:1024
	ds_read_b128 v[176:179], v152 offset:2048
	ds_read_b128 v[180:183], v152 offset:3072
	v_lshl_add_u64 v[152:153], s[24:25], 0, v[148:149]
	s_add_i32 m0, s35, 0xc000
	ds_read_b128 v[184:187], v174
	ds_read_b128 v[188:191], v174 offset:1024
	ds_read_b128 v[192:195], v174 offset:2048
	ds_read_b128 v[196:199], v174 offset:3072
	ds_read_b128 v[200:203], v174 offset:4096
	ds_read_b128 v[210:213], v174 offset:5120
	ds_read_b128 v[214:217], v174 offset:6144
	ds_read_b128 v[218:221], v174 offset:7168
	global_load_lds_dwordx4 v[152:153], off
	v_lshl_add_u64 v[152:153], s[24:25], 0, v[150:151]
	s_add_i32 m0, s35, 0xe000
	s_nop 0
	global_load_lds_dwordx4 v[152:153], off
	s_waitcnt vmcnt(8)
	s_waitcnt lgkmcnt(0)
	s_barrier
	s_setprio 1
	v_mfma_f32_16x16x32_bf16 v[142:145], v[26:29], v[184:187], v[142:145]
	v_mfma_f32_16x16x32_bf16 v[138:141], v[46:49], v[184:187], v[138:141]
	v_mfma_f32_16x16x32_bf16 v[126:129], v[26:29], v[192:195], v[126:129]
	v_mfma_f32_16x16x32_bf16 v[122:125], v[46:49], v[192:195], v[122:125]
	v_mfma_f32_16x16x32_bf16 v[110:113], v[26:29], v[200:203], v[110:113]
	v_mfma_f32_16x16x32_bf16 v[106:109], v[46:49], v[200:203], v[106:109]
	v_mfma_f32_16x16x32_bf16 v[94:97], v[26:29], v[214:217], v[94:97]
	v_mfma_f32_16x16x32_bf16 v[90:93], v[46:49], v[214:217], v[90:93]
	v_mfma_f32_16x16x32_bf16 v[142:145], v[30:33], v[188:191], v[142:145]
	v_mfma_f32_16x16x32_bf16 v[138:141], v[50:53], v[188:191], v[138:141]
	v_mfma_f32_16x16x32_bf16 v[126:129], v[30:33], v[196:199], v[126:129]
	v_mfma_f32_16x16x32_bf16 v[122:125], v[50:53], v[196:199], v[122:125]
	v_mfma_f32_16x16x32_bf16 v[110:113], v[30:33], v[210:213], v[110:113]
	v_mfma_f32_16x16x32_bf16 v[106:109], v[50:53], v[210:213], v[106:109]
	v_mfma_f32_16x16x32_bf16 v[94:97], v[30:33], v[218:221], v[94:97]
	v_mfma_f32_16x16x32_bf16 v[90:93], v[50:53], v[218:221], v[90:93]
	s_setprio 0
	s_setprio 1
	v_mfma_f32_16x16x32_bf16 v[134:137], v[162:165], v[184:187], v[134:137]
	v_mfma_f32_16x16x32_bf16 v[130:133], v[176:179], v[184:187], v[130:133]
	v_mfma_f32_16x16x32_bf16 v[118:121], v[162:165], v[192:195], v[118:121]
	v_mfma_f32_16x16x32_bf16 v[114:117], v[176:179], v[192:195], v[114:117]
	v_mfma_f32_16x16x32_bf16 v[102:105], v[162:165], v[200:203], v[102:105]
	v_mfma_f32_16x16x32_bf16 v[98:101], v[176:179], v[200:203], v[98:101]
	v_mfma_f32_16x16x32_bf16 v[86:89], v[162:165], v[214:217], v[86:89]
	v_mfma_f32_16x16x32_bf16 v[82:85], v[176:179], v[214:217], v[82:85]
	v_mfma_f32_16x16x32_bf16 v[134:137], v[166:169], v[188:191], v[134:137]
	v_mfma_f32_16x16x32_bf16 v[130:133], v[180:183], v[188:191], v[130:133]
	v_mfma_f32_16x16x32_bf16 v[118:121], v[166:169], v[196:199], v[118:121]
	v_mfma_f32_16x16x32_bf16 v[114:117], v[180:183], v[196:199], v[114:117]
	v_mfma_f32_16x16x32_bf16 v[102:105], v[166:169], v[210:213], v[102:105]
	v_mfma_f32_16x16x32_bf16 v[98:101], v[180:183], v[210:213], v[98:101]
	v_mfma_f32_16x16x32_bf16 v[86:89], v[166:169], v[218:221], v[86:89]
	v_mfma_f32_16x16x32_bf16 v[82:85], v[180:183], v[218:221], v[82:85]
	s_barrier
	s_setprio 0
	s_add_i32 s45, s45, s34
	v_lshl_add_u64 v[152:153], s[26:27], 0, v[0:1]
	s_mov_b32 m0, s45
	ds_read_b128 v[184:187], v174 offset:16384
	ds_read_b128 v[188:191], v174 offset:17408
	ds_read_b128 v[192:195], v174 offset:18432
	ds_read_b128 v[196:199], v174 offset:19456
	ds_read_b128 v[200:203], v174 offset:20480
	ds_read_b128 v[210:213], v174 offset:21504
	ds_read_b128 v[214:217], v174 offset:22528
	ds_read_b128 v[218:221], v174 offset:23552
	global_load_lds_dwordx4 v[152:153], off
	s_add_i32 m0, s45, 0x2000
	s_add_u32 s64, s26, 0x40000
	v_lshl_add_u64 v[222:223], s[26:27], 0, v[146:147]
	s_addc_u32 s65, s27, 0
	s_add_i32 s45, s68, s34
	global_load_lds_dwordx4 v[222:223], off
	v_lshl_add_u64 v[224:225], s[64:65], 0, v[0:1]
	s_mov_b32 m0, s45
	v_lshl_add_u64 v[226:227], s[28:29], 0, v[146:147]
	global_load_lds_dwordx4 v[224:225], off
	v_lshl_add_u64 v[224:225], s[64:65], 0, v[146:147]
	s_add_i32 m0, s45, 0x2000
	s_nop 0
	global_load_lds_dwordx4 v[224:225], off
	v_lshl_add_u64 v[224:225], s[28:29], 0, v[0:1]
	s_mov_b32 m0, s35
	s_nop 0
	global_load_lds_dwordx4 v[224:225], off
	s_mov_b32 m0, s36
	s_nop 0
	global_load_lds_dwordx4 v[226:227], off
	s_waitcnt vmcnt(8)
	s_waitcnt lgkmcnt(0)
	s_barrier
; #define PG8_STAGE(bufoff, gbase, voff) do { _Pragma("unroll") for (int _i = 0; _i < 2; ++_i) \
;         __builtin_amdgcn_global_load_lds((const unsigned*)((const char*)(gbase) + (voff)[_i]), (PG8_LAS unsigned*)(lds + (bufoff) + ldsw + _i * 8192), 16, 0, 0); } while (0)
; #define PG8_LDA(dst, b, h) do { _Pragma("unroll") for (int m = 0; m < 4; ++m) _Pragma("unroll") for (int k = 0; k < 2; ++k) dst[m][k] = *(const PG8_LAS bf16x8*)(lds + PG8_SA(b, h) + aoff + m * 2048 + k * 1024); } while (0)
; #define PG8_LDB(dst, b, h) do { _Pragma("unroll") for (int n = 0; n < 2; ++n) _Pragma("unroll") for (int k = 0; k < 2; ++k) dst[n][k] = *(const PG8_LAS bf16x8*)(lds + PG8_SB(b, h) + boff + n * 2048 + k * 1024); } while (0)
; #define PG8_MMA(ai, bj, At, Bt) do { __builtin_amdgcn_s_setprio(1); _Pragma("unroll") for (int m = 0; m < 4; ++m) _Pragma("unroll") for (int n = 0; n < 2; ++n) _Pragma("unroll") for (int k = 0; k < 2; ++k) \
;         acc[ai][bj][m][n] = __builtin_amdgcn_mfma_f32_16x16x32_bf16(Bt[n][k], At[m][k], acc[ai][bj][m][n], 0, 0, 0); __builtin_amdgcn_s_setprio(0); } while (0)
; #define PG8_WAIT_V(n) asm volatile("s_waitcnt vmcnt(" #n ")" ::: "memory")
; #define PG8_WAIT_L(n) asm volatile("s_waitcnt lgkmcnt(" #n ")" ::: "memory")
; #define PG8_BAR __builtin_amdgcn_s_barrier()
; #define PG8_SCHED __builtin_amdgcn_sched_barrier(0)
; template <class Epi, class Sched, bool ALIGN_EPI = false, bool SP2 = false>
; __device__ __forceinline__ void gemm_phase(PG8_LAS unsigned char* lds, const Gemm g, const Sched& S, const Epi& E, const int wave_s) {
;     ...
;             PG8_WAIT_V(8); PG8_WAIT_L(0); PG8_BAR; PG8_MMA(1, 0, At, B0); PG8_MMA(1, 1, At, B1); PG8_BAR; PG8_SCHED;
;             PG8_LDB(B0, 1, 0); PG8_LDB(B1, 1, 1); PG8_SCHED; PG8_LDA(At, 1, 0); PG8_STAGE(PG8_SA(0, 1), a2 + hstep, voffA);
;             PG8_WAIT_V(8); PG8_WAIT_L(0); PG8_BAR; PG8_MMA(0, 0, At, B0); PG8_MMA(0, 1, At, B1); PG8_BAR; PG8_SCHED;
	s_setprio 1
	v_mfma_f32_16x16x32_bf16 v[78:81], v[26:29], v[184:187], v[78:81]
	v_mfma_f32_16x16x32_bf16 v[74:77], v[46:49], v[184:187], v[74:77]
	v_mfma_f32_16x16x32_bf16 v[62:65], v[26:29], v[192:195], v[62:65]
	v_mfma_f32_16x16x32_bf16 v[58:61], v[46:49], v[192:195], v[58:61]
	v_mfma_f32_16x16x32_bf16 v[38:41], v[26:29], v[200:203], v[38:41]
	v_mfma_f32_16x16x32_bf16 v[34:37], v[46:49], v[200:203], v[34:37]
	v_mfma_f32_16x16x32_bf16 v[14:17], v[26:29], v[214:217], v[14:17]
	v_mfma_f32_16x16x32_bf16 v[10:13], v[46:49], v[214:217], v[10:13]
	v_mfma_f32_16x16x32_bf16 v[78:81], v[30:33], v[188:191], v[78:81]
	v_mfma_f32_16x16x32_bf16 v[74:77], v[50:53], v[188:191], v[74:77]
	v_mfma_f32_16x16x32_bf16 v[62:65], v[30:33], v[196:199], v[62:65]
	v_mfma_f32_16x16x32_bf16 v[58:61], v[50:53], v[196:199], v[58:61]
	v_mfma_f32_16x16x32_bf16 v[38:41], v[30:33], v[210:213], v[38:41]
	v_mfma_f32_16x16x32_bf16 v[34:37], v[50:53], v[210:213], v[34:37]
	v_mfma_f32_16x16x32_bf16 v[14:17], v[30:33], v[218:221], v[14:17]
	v_mfma_f32_16x16x32_bf16 v[10:13], v[50:53], v[218:221], v[10:13]
	s_setprio 0
	s_setprio 1
	v_mfma_f32_16x16x32_bf16 v[42:45], v[176:179], v[192:195], v[42:45]
	v_mfma_f32_16x16x32_bf16 v[22:25], v[162:165], v[200:203], v[22:25]
	v_mfma_f32_16x16x32_bf16 v[18:21], v[176:179], v[200:203], v[18:21]
	v_mfma_f32_16x16x32_bf16 v[6:9], v[162:165], v[214:217], v[6:9]
	v_mfma_f32_16x16x32_bf16 v[2:5], v[176:179], v[214:217], v[2:5]
	v_mfma_f32_16x16x32_bf16 v[26:29], v[162:165], v[184:187], v[70:73]
	v_mfma_f32_16x16x32_bf16 v[30:33], v[176:179], v[184:187], v[66:69]
	v_mfma_f32_16x16x32_bf16 v[46:49], v[162:165], v[192:195], v[54:57]
	v_mfma_f32_16x16x32_bf16 v[42:45], v[180:183], v[196:199], v[42:45]
	v_mfma_f32_16x16x32_bf16 v[22:25], v[166:169], v[210:213], v[22:25]
	v_mfma_f32_16x16x32_bf16 v[18:21], v[180:183], v[210:213], v[18:21]
	v_mfma_f32_16x16x32_bf16 v[6:9], v[166:169], v[218:221], v[6:9]
	v_mfma_f32_16x16x32_bf16 v[2:5], v[180:183], v[218:221], v[2:5]
	v_mfma_f32_16x16x32_bf16 v[26:29], v[166:169], v[188:191], v[26:29]
	v_mfma_f32_16x16x32_bf16 v[30:33], v[180:183], v[188:191], v[30:33]
	v_mfma_f32_16x16x32_bf16 v[46:49], v[166:169], v[196:199], v[46:49]
	s_barrier
	s_setprio 0
	s_add_i32 s45, 0, 0x18000
	s_add_i32 s64, 0, 0x1c000
	v_add_u32_e32 v70, s45, v171
	v_add_u32_e32 v175, s64, v171
	ds_read_b128 v[50:53], v70
	ds_read_b128 v[54:57], v70 offset:1024
	ds_read_b128 v[66:69], v70 offset:2048
	ds_read_b128 v[70:73], v70 offset:3072
	ds_read_b128 v[162:165], v175
	ds_read_b128 v[166:169], v175 offset:1024
	ds_read_b128 v[176:179], v175 offset:2048
	ds_read_b128 v[180:183], v175 offset:3072
	s_add_u32 s28, s28, 0x40000
	s_addc_u32 s29, s29, 0
	s_mov_b32 m0, s37
	v_lshl_add_u64 v[228:229], s[28:29], 0, v[0:1]
	ds_read_b128 v[184:187], v174 offset:32768
	ds_read_b128 v[188:191], v174 offset:33792
	ds_read_b128 v[192:195], v174 offset:34816
	ds_read_b128 v[196:199], v174 offset:35840
	ds_read_b128 v[200:203], v174 offset:36864
	ds_read_b128 v[210:213], v174 offset:37888
	ds_read_b128 v[214:217], v174 offset:38912
	ds_read_b128 v[218:221], v174 offset:39936
	global_load_lds_dwordx4 v[228:229], off
	v_lshl_add_u64 v[228:229], s[28:29], 0, v[146:147]
	s_mov_b32 m0, s38
	s_nop 0
	global_load_lds_dwordx4 v[228:229], off
	s_waitcnt vmcnt(8)
	s_waitcnt lgkmcnt(0)
	s_barrier
	s_setprio 1
	v_mfma_f32_16x16x32_bf16 v[142:145], v[50:53], v[184:187], v[142:145]
	v_mfma_f32_16x16x32_bf16 v[138:141], v[66:69], v[184:187], v[138:141]
	v_mfma_f32_16x16x32_bf16 v[126:129], v[50:53], v[192:195], v[126:129]
	v_mfma_f32_16x16x32_bf16 v[122:125], v[66:69], v[192:195], v[122:125]
	v_mfma_f32_16x16x32_bf16 v[110:113], v[50:53], v[200:203], v[110:113]
	v_mfma_f32_16x16x32_bf16 v[106:109], v[66:69], v[200:203], v[106:109]
	v_mfma_f32_16x16x32_bf16 v[94:97], v[50:53], v[214:217], v[94:97]
	v_mfma_f32_16x16x32_bf16 v[90:93], v[66:69], v[214:217], v[90:93]
	v_mfma_f32_16x16x32_bf16 v[142:145], v[54:57], v[188:191], v[142:145]
	v_mfma_f32_16x16x32_bf16 v[138:141], v[70:73], v[188:191], v[138:141]
	v_mfma_f32_16x16x32_bf16 v[126:129], v[54:57], v[196:199], v[126:129]
	v_mfma_f32_16x16x32_bf16 v[122:125], v[70:73], v[196:199], v[122:125]
	v_mfma_f32_16x16x32_bf16 v[110:113], v[54:57], v[210:213], v[110:113]
	v_mfma_f32_16x16x32_bf16 v[106:109], v[70:73], v[210:213], v[106:109]
	v_mfma_f32_16x16x32_bf16 v[94:97], v[54:57], v[218:221], v[94:97]
	v_mfma_f32_16x16x32_bf16 v[90:93], v[70:73], v[218:221], v[90:93]
	s_setprio 0
	s_setprio 1
	v_mfma_f32_16x16x32_bf16 v[134:137], v[162:165], v[184:187], v[134:137]
	v_mfma_f32_16x16x32_bf16 v[130:133], v[176:179], v[184:187], v[130:133]
	v_mfma_f32_16x16x32_bf16 v[118:121], v[162:165], v[192:195], v[118:121]
	v_mfma_f32_16x16x32_bf16 v[114:117], v[176:179], v[192:195], v[114:117]
	v_mfma_f32_16x16x32_bf16 v[102:105], v[162:165], v[200:203], v[102:105]
	v_mfma_f32_16x16x32_bf16 v[98:101], v[176:179], v[200:203], v[98:101]
	v_mfma_f32_16x16x32_bf16 v[86:89], v[162:165], v[214:217], v[86:89]
	v_mfma_f32_16x16x32_bf16 v[82:85], v[176:179], v[214:217], v[82:85]
	v_mfma_f32_16x16x32_bf16 v[134:137], v[166:169], v[188:191], v[134:137]
	v_mfma_f32_16x16x32_bf16 v[130:133], v[180:183], v[188:191], v[130:133]
	v_mfma_f32_16x16x32_bf16 v[118:121], v[166:169], v[196:199], v[118:121]
	v_mfma_f32_16x16x32_bf16 v[114:117], v[180:183], v[196:199], v[114:117]
	v_mfma_f32_16x16x32_bf16 v[102:105], v[166:169], v[210:213], v[102:105]
	v_mfma_f32_16x16x32_bf16 v[98:101], v[180:183], v[210:213], v[98:101]
	v_mfma_f32_16x16x32_bf16 v[86:89], v[166:169], v[218:221], v[86:89]
	v_mfma_f32_16x16x32_bf16 v[82:85], v[180:183], v[218:221], v[82:85]
	s_barrier
; #define PG8_STAGE(bufoff, gbase, voff) do { _Pragma("unroll") for (int _i = 0; _i < 2; ++_i) \
;         __builtin_amdgcn_global_load_lds((const unsigned*)((const char*)(gbase) + (voff)[_i]), (PG8_LAS unsigned*)(lds + (bufoff) + ldsw + _i * 8192), 16, 0, 0); } while (0)
; #define PG8_LDA(dst, b, h) do { _Pragma("unroll") for (int m = 0; m < 4; ++m) _Pragma("unroll") for (int k = 0; k < 2; ++k) dst[m][k] = *(const PG8_LAS bf16x8*)(lds + PG8_SA(b, h) + aoff + m * 2048 + k * 1024); } while (0)
; #define PG8_MMA(ai, bj, At, Bt) do { __builtin_amdgcn_s_setprio(1); _Pragma("unroll") for (int m = 0; m < 4; ++m) _Pragma("unroll") for (int n = 0; n < 2; ++n) _Pragma("unroll") for (int k = 0; k < 2; ++k) \
;         acc[ai][bj][m][n] = __builtin_amdgcn_mfma_f32_16x16x32_bf16(Bt[n][k], At[m][k], acc[ai][bj][m][n], 0, 0, 0); __builtin_amdgcn_s_setprio(0); } while (0)
; #define PG8_WAIT_V(n) asm volatile("s_waitcnt vmcnt(" #n ")" ::: "memory")
; #define PG8_WAIT_L(n) asm volatile("s_waitcnt lgkmcnt(" #n ")" ::: "memory")
; #define PG8_BAR __builtin_amdgcn_s_barrier()
; #define PG8_SCHED __builtin_amdgcn_sched_barrier(0)
; template <class Epi, class Sched, bool ALIGN_EPI = false, bool SP2 = false>
; __device__ __forceinline__ void gemm_phase(PG8_LAS unsigned char* lds, const Gemm g, const Sched& S, const Epi& E, const int wave_s) {
;     ...
;             PG8_LDA(At, 1, 1); PG8_STAGE(PG8_SB(1, 0), b3, voffB); PG8_STAGE(PG8_SB(1, 1), b3 + hstep, voffB); PG8_STAGE(PG8_SA(1, 0), a3, voffA);
;             PG8_WAIT_V(8); PG8_WAIT_L(0); PG8_BAR; PG8_MMA(1, 0, At, B0); PG8_MMA(1, 1, At, B1); PG8_BAR; PG8_SCHED;
;     ...
;         if constexpr (ALIGN_EPI) { if (wr == 0) PG8_BAR; }
	s_setprio 0
	s_add_i32 s28, s45, s34
	v_lshl_add_u64 v[152:153], v[152:153], 0, s[70:71]
	s_mov_b32 m0, s28
	ds_read_b128 v[184:187], v174 offset:49152
	ds_read_b128 v[188:191], v174 offset:50176
	ds_read_b128 v[192:195], v174 offset:51200
	ds_read_b128 v[196:199], v174 offset:52224
	ds_read_b128 v[200:203], v174 offset:53248
	ds_read_b128 v[210:213], v174 offset:54272
	ds_read_b128 v[214:217], v174 offset:55296
	ds_read_b128 v[218:221], v174 offset:56320
	global_load_lds_dwordx4 v[152:153], off
	s_add_i32 m0, s28, 0x2000
	s_add_u32 s26, s26, 0x40080
	v_lshl_add_u64 v[152:153], v[222:223], 0, s[70:71]
	s_addc_u32 s27, s27, 0
	s_add_i32 s28, s64, s34
	global_load_lds_dwordx4 v[152:153], off
	v_lshl_add_u64 v[152:153], s[26:27], 0, v[0:1]
	s_mov_b32 m0, s28
	s_nop 0
	global_load_lds_dwordx4 v[152:153], off
	v_lshl_add_u64 v[152:153], s[26:27], 0, v[146:147]
	s_add_i32 m0, s28, 0x2000
	s_nop 0
	global_load_lds_dwordx4 v[152:153], off
	v_lshl_add_u64 v[152:153], v[224:225], 0, s[70:71]
	s_mov_b32 m0, s40
	s_nop 0
	global_load_lds_dwordx4 v[152:153], off
	v_lshl_add_u64 v[152:153], v[226:227], 0, s[70:71]
	s_mov_b32 m0, s41
	s_nop 0
	global_load_lds_dwordx4 v[152:153], off
	s_waitcnt vmcnt(8)
	s_waitcnt lgkmcnt(0)
	s_barrier
	s_setprio 1
	v_mfma_f32_16x16x32_bf16 v[78:81], v[50:53], v[184:187], v[78:81]
	v_mfma_f32_16x16x32_bf16 v[74:77], v[66:69], v[184:187], v[74:77]
	v_mfma_f32_16x16x32_bf16 v[62:65], v[50:53], v[192:195], v[62:65]
	v_mfma_f32_16x16x32_bf16 v[58:61], v[66:69], v[192:195], v[58:61]
	v_mfma_f32_16x16x32_bf16 v[38:41], v[50:53], v[200:203], v[38:41]
	v_mfma_f32_16x16x32_bf16 v[34:37], v[66:69], v[200:203], v[34:37]
	v_mfma_f32_16x16x32_bf16 v[14:17], v[50:53], v[214:217], v[14:17]
	v_mfma_f32_16x16x32_bf16 v[10:13], v[66:69], v[214:217], v[10:13]
	v_mfma_f32_16x16x32_bf16 v[78:81], v[54:57], v[188:191], v[78:81]
	v_mfma_f32_16x16x32_bf16 v[74:77], v[70:73], v[188:191], v[74:77]
	v_mfma_f32_16x16x32_bf16 v[62:65], v[54:57], v[196:199], v[62:65]
	v_mfma_f32_16x16x32_bf16 v[58:61], v[70:73], v[196:199], v[58:61]
	v_mfma_f32_16x16x32_bf16 v[38:41], v[54:57], v[210:213], v[38:41]
	v_mfma_f32_16x16x32_bf16 v[34:37], v[70:73], v[210:213], v[34:37]
	v_mfma_f32_16x16x32_bf16 v[14:17], v[54:57], v[218:221], v[14:17]
	v_mfma_f32_16x16x32_bf16 v[10:13], v[70:73], v[218:221], v[10:13]
	s_setprio 0
	s_setprio 1
	v_mfma_f32_16x16x32_bf16 v[26:29], v[162:165], v[184:187], v[26:29]
	v_mfma_f32_16x16x32_bf16 v[70:73], v[166:169], v[188:191], v[26:29]
	v_mfma_f32_16x16x32_bf16 v[26:29], v[176:179], v[184:187], v[30:33]
	v_mfma_f32_16x16x32_bf16 v[66:69], v[180:183], v[188:191], v[26:29]
	v_mfma_f32_16x16x32_bf16 v[26:29], v[162:165], v[192:195], v[46:49]
	v_mfma_f32_16x16x32_bf16 v[54:57], v[166:169], v[196:199], v[26:29]
	v_mfma_f32_16x16x32_bf16 v[26:29], v[176:179], v[192:195], v[42:45]
	v_mfma_f32_16x16x32_bf16 v[22:25], v[162:165], v[200:203], v[22:25]
	v_mfma_f32_16x16x32_bf16 v[18:21], v[176:179], v[200:203], v[18:21]
	v_mfma_f32_16x16x32_bf16 v[6:9], v[162:165], v[214:217], v[6:9]
	v_mfma_f32_16x16x32_bf16 v[2:5], v[176:179], v[214:217], v[2:5]
	v_mfma_f32_16x16x32_bf16 v[42:45], v[180:183], v[196:199], v[26:29]
	v_mfma_f32_16x16x32_bf16 v[22:25], v[166:169], v[210:213], v[22:25]
	v_mfma_f32_16x16x32_bf16 v[18:21], v[180:183], v[210:213], v[18:21]
	v_mfma_f32_16x16x32_bf16 v[6:9], v[166:169], v[218:221], v[6:9]
	v_mfma_f32_16x16x32_bf16 v[2:5], v[180:183], v[218:221], v[2:5]
	s_barrier
	s_setprio 0
	s_add_i32 s50, s50, 2
	s_add_u32 s24, s24, 0x100
	s_addc_u32 s25, s25, 0
	s_add_u32 s58, s58, 0x100
	s_addc_u32 s59, s59, 0
	s_cmp_gt_u32 s50, 13
	s_cbranch_scc0 .LBB0_734
	s_and_b64 vcc, exec, s[14:15]
	s_cbranch_vccz .LBB0_737
	s_barrier

; #define PG8_STAGE(bufoff, gbase, voff) do { _Pragma("unroll") for (int _i = 0; _i < 2; ++_i) \
;         __builtin_amdgcn_global_load_lds((const unsigned*)((const char*)(gbase) + (voff)[_i]), (PG8_LAS unsigned*)(lds + (bufoff) + ldsw + _i * 8192), 16, 0, 0); } while (0)
; #define PG8_LDA(dst, b, h) do { _Pragma("unroll") for (int m = 0; m < 4; ++m) _Pragma("unroll") for (int k = 0; k < 2; ++k) dst[m][k] = *(const PG8_LAS bf16x8*)(lds + PG8_SA(b, h) + aoff + m * 2048 + k * 1024); } while (0)
; #define PG8_LDB(dst, b, h) do { _Pragma("unroll") for (int n = 0; n < 2; ++n) _Pragma("unroll") for (int k = 0; k < 2; ++k) dst[n][k] = *(const PG8_LAS bf16x8*)(lds + PG8_SB(b, h) + boff + n * 2048 + k * 1024); } while (0)
; #define PG8_MMA(ai, bj, At, Bt) do { __builtin_amdgcn_s_setprio(1); _Pragma("unroll") for (int m = 0; m < 4; ++m) _Pragma("unroll") for (int n = 0; n < 2; ++n) _Pragma("unroll") for (int k = 0; k < 2; ++k) \
;         acc[ai][bj][m][n] = __builtin_amdgcn_mfma_f32_16x16x32_bf16(Bt[n][k], At[m][k], acc[ai][bj][m][n], 0, 0, 0); __builtin_amdgcn_s_setprio(0); } while (0)
; #define PG8_WAIT_V(n) asm volatile("s_waitcnt vmcnt(" #n ")" ::: "memory")
; #define PG8_WAIT_L(n) asm volatile("s_waitcnt lgkmcnt(" #n ")" ::: "memory")
; #define PG8_BAR __builtin_amdgcn_s_barrier()
; template <class Epi, class Sched, bool ALIGN_EPI = false, bool SP2 = false>
; __device__ __forceinline__ void gemm_phase(PG8_LAS unsigned char* lds, const Gemm g, const Sched& S, const Epi& E, const int wave_s) {
;     ...
;         for (int t = 0; t < nt; t += 2) {
;             const bool last = (t == nt - 2);
;             const char* a1 = cA + (size_t)(t + 1) * kstep;
;             const char* a2 = last ? nA : cA + (size_t)(t + 2) * kstep; const char* b2 = last ? nB : cB + (size_t)(t + 2) * kstep;
;             const char* a3 = a2 + kstep; const char* b3 = b2 + kstep;
;             if (last && has_next) S.a_ready(nxt);
;             if constexpr (SP2) {
;             PG8_LDB(B0, 0, 0); PG8_LDB(B1, 0, 1); PG8_SCHED; PG8_LDA(At, 0, 0); PG8_STAGE(PG8_SA(1, 1), a1 + hstep, voffA);
;             PG8_WAIT_V(8); PG8_WAIT_L(0); PG8_BAR; PG8_MMA(0, 0, At, B0); PG8_MMA(0, 1, At, B1); PG8_BAR; PG8_SCHED;
;             PG8_LDA(At, 0, 1); PG8_STAGE(PG8_SB(0, 0), b2, voffB); PG8_STAGE(PG8_SB(0, 1), b2 + hstep, voffB); PG8_STAGE(PG8_SA(0, 0), a2, voffA);
.LBB0_806:
	s_add_u32 s8, s10, 0x100
	s_addc_u32 s9, s11, 0
	s_add_i32 s45, 0, 0x10000
	s_cmp_eq_u32 s75, 40
	s_cselect_b32 s49, s37, s9
	s_cselect_b32 s48, s36, s8
	v_add_u32_e32 v0, s45, v203
	s_cselect_b32 s41, s39, vcc_hi
	s_cselect_b32 s40, s38, vcc_lo
	s_add_i32 s80, 0, 0x14000
	ds_read_b128 v[122:125], v0
	ds_read_b128 v[126:129], v0 offset:1024
	ds_read_b128 v[138:141], v0 offset:2048
	ds_read_b128 v[142:145], v0 offset:3072
	v_add_u32_e32 v0, s80, v203
	ds_read_b128 v[146:149], v0
	ds_read_b128 v[150:153], v0 offset:1024
	ds_read_b128 v[174:177], v0 offset:2048
	ds_read_b128 v[178:181], v0 offset:3072
	v_lshl_add_u64 v[226:227], s[10:11], 0, v[170:171]
	s_add_i32 m0, s76, 0xc000
	ds_read_b128 v[182:185], v212
	ds_read_b128 v[186:189], v212 offset:1024
	ds_read_b128 v[190:193], v212 offset:2048
	ds_read_b128 v[194:197], v212 offset:3072
	ds_read_b128 v[198:201], v212 offset:4096
	ds_read_b128 v[214:217], v212 offset:5120
	ds_read_b128 v[218:221], v212 offset:6144
	ds_read_b128 v[222:225], v212 offset:7168
	global_load_lds_dwordx4 v[226:227], off
	v_lshl_add_u64 v[226:227], s[10:11], 0, v[172:173]
	s_add_i32 m0, s76, 0xe000
	s_nop 0
	global_load_lds_dwordx4 v[226:227], off
	s_waitcnt vmcnt(8)
	s_waitcnt lgkmcnt(0)
	s_barrier
	s_setprio 1
	v_mfma_f32_16x16x32_bf16 v[6:9], v[122:125], v[182:185], v[6:9]
	v_mfma_f32_16x16x32_bf16 v[2:5], v[138:141], v[182:185], v[2:5]
	v_mfma_f32_16x16x32_bf16 v[134:137], v[122:125], v[190:193], v[134:137]
	v_mfma_f32_16x16x32_bf16 v[130:133], v[138:141], v[190:193], v[130:133]
	v_mfma_f32_16x16x32_bf16 v[118:121], v[122:125], v[198:201], v[118:121]
	v_mfma_f32_16x16x32_bf16 v[114:117], v[138:141], v[198:201], v[114:117]
	v_mfma_f32_16x16x32_bf16 v[110:113], v[122:125], v[218:221], v[110:113]
	v_mfma_f32_16x16x32_bf16 v[106:109], v[138:141], v[218:221], v[106:109]
	v_mfma_f32_16x16x32_bf16 v[6:9], v[126:129], v[186:189], v[6:9]
	v_mfma_f32_16x16x32_bf16 v[2:5], v[142:145], v[186:189], v[2:5]
	v_mfma_f32_16x16x32_bf16 v[134:137], v[126:129], v[194:197], v[134:137]
	v_mfma_f32_16x16x32_bf16 v[130:133], v[142:145], v[194:197], v[130:133]
	v_mfma_f32_16x16x32_bf16 v[118:121], v[126:129], v[214:217], v[118:121]
	v_mfma_f32_16x16x32_bf16 v[114:117], v[142:145], v[214:217], v[114:117]
	v_mfma_f32_16x16x32_bf16 v[110:113], v[126:129], v[222:225], v[110:113]
	v_mfma_f32_16x16x32_bf16 v[106:109], v[142:145], v[222:225], v[106:109]
	s_setprio 0
	s_setprio 1
	v_mfma_f32_16x16x32_bf16 v[70:73], v[146:149], v[182:185], v[70:73]
	v_mfma_f32_16x16x32_bf16 v[66:69], v[174:177], v[182:185], v[66:69]
	v_mfma_f32_16x16x32_bf16 v[62:65], v[146:149], v[190:193], v[62:65]
	v_mfma_f32_16x16x32_bf16 v[58:61], v[174:177], v[190:193], v[58:61]
	v_mfma_f32_16x16x32_bf16 v[54:57], v[146:149], v[198:201], v[54:57]
	v_mfma_f32_16x16x32_bf16 v[50:53], v[174:177], v[198:201], v[50:53]
	v_mfma_f32_16x16x32_bf16 v[46:49], v[146:149], v[218:221], v[46:49]
	v_mfma_f32_16x16x32_bf16 v[42:45], v[174:177], v[218:221], v[42:45]
	v_mfma_f32_16x16x32_bf16 v[70:73], v[150:153], v[186:189], v[70:73]
	v_mfma_f32_16x16x32_bf16 v[66:69], v[178:181], v[186:189], v[66:69]
	v_mfma_f32_16x16x32_bf16 v[62:65], v[150:153], v[194:197], v[62:65]
	v_mfma_f32_16x16x32_bf16 v[58:61], v[178:181], v[194:197], v[58:61]
	v_mfma_f32_16x16x32_bf16 v[54:57], v[150:153], v[214:217], v[54:57]
	v_mfma_f32_16x16x32_bf16 v[50:53], v[178:181], v[214:217], v[50:53]
	v_mfma_f32_16x16x32_bf16 v[46:49], v[150:153], v[222:225], v[46:49]
	v_mfma_f32_16x16x32_bf16 v[42:45], v[178:181], v[222:225], v[42:45]
	s_barrier
	s_setprio 0
	s_add_i32 s10, s45, s44
	v_lshl_add_u64 v[226:227], s[40:41], 0, v[166:167]
	s_mov_b32 m0, s10
	ds_read_b128 v[182:185], v212 offset:16384
	ds_read_b128 v[186:189], v212 offset:17408
	ds_read_b128 v[190:193], v212 offset:18432
	ds_read_b128 v[194:197], v212 offset:19456
	ds_read_b128 v[198:201], v212 offset:20480
	ds_read_b128 v[214:217], v212 offset:21504
	ds_read_b128 v[218:221], v212 offset:22528
	ds_read_b128 v[222:225], v212 offset:23552
	global_load_lds_dwordx4 v[226:227], off
	s_add_i32 m0, s10, 0x2000
	s_add_u32 s10, s40, 0xb0000
	v_lshl_add_u64 v[228:229], s[40:41], 0, v[162:163]
	s_addc_u32 s11, s41, 0
	s_add_i32 s45, s80, s44
	global_load_lds_dwordx4 v[228:229], off
	v_lshl_add_u64 v[230:231], s[10:11], 0, v[166:167]
	s_mov_b32 m0, s45
	v_lshl_add_u64 v[232:233], s[48:49], 0, v[164:165]
	global_load_lds_dwordx4 v[230:231], off
	v_lshl_add_u64 v[230:231], s[10:11], 0, v[162:163]
	s_add_i32 m0, s45, 0x2000
	s_nop 0
	global_load_lds_dwordx4 v[230:231], off
	v_lshl_add_u64 v[230:231], s[48:49], 0, v[168:169]
	s_mov_b32 m0, s76
	s_nop 0
	global_load_lds_dwordx4 v[230:231], off
	s_mov_b32 m0, s77
	s_nop 0
	global_load_lds_dwordx4 v[232:233], off
	s_waitcnt vmcnt(8)
	s_waitcnt lgkmcnt(0)
	s_barrier
; #define PG8_STAGE(bufoff, gbase, voff) do { _Pragma("unroll") for (int _i = 0; _i < 2; ++_i) \
;         __builtin_amdgcn_global_load_lds((const unsigned*)((const char*)(gbase) + (voff)[_i]), (PG8_LAS unsigned*)(lds + (bufoff) + ldsw + _i * 8192), 16, 0, 0); } while (0)
; #define PG8_LDA(dst, b, h) do { _Pragma("unroll") for (int m = 0; m < 4; ++m) _Pragma("unroll") for (int k = 0; k < 2; ++k) dst[m][k] = *(const PG8_LAS bf16x8*)(lds + PG8_SA(b, h) + aoff + m * 2048 + k * 1024); } while (0)
; #define PG8_LDB(dst, b, h) do { _Pragma("unroll") for (int n = 0; n < 2; ++n) _Pragma("unroll") for (int k = 0; k < 2; ++k) dst[n][k] = *(const PG8_LAS bf16x8*)(lds + PG8_SB(b, h) + boff + n * 2048 + k * 1024); } while (0)
; #define PG8_MMA(ai, bj, At, Bt) do { __builtin_amdgcn_s_setprio(1); _Pragma("unroll") for (int m = 0; m < 4; ++m) _Pragma("unroll") for (int n = 0; n < 2; ++n) _Pragma("unroll") for (int k = 0; k < 2; ++k) \
;         acc[ai][bj][m][n] = __builtin_amdgcn_mfma_f32_16x16x32_bf16(Bt[n][k], At[m][k], acc[ai][bj][m][n], 0, 0, 0); __builtin_amdgcn_s_setprio(0); } while (0)
; #define PG8_WAIT_V(n) asm volatile("s_waitcnt vmcnt(" #n ")" ::: "memory")
; #define PG8_WAIT_L(n) asm volatile("s_waitcnt lgkmcnt(" #n ")" ::: "memory")
; #define PG8_BAR __builtin_amdgcn_s_barrier()
; #define PG8_SCHED __builtin_amdgcn_sched_barrier(0)
; template <class Epi, class Sched, bool ALIGN_EPI = false, bool SP2 = false>
; __device__ __forceinline__ void gemm_phase(PG8_LAS unsigned char* lds, const Gemm g, const Sched& S, const Epi& E, const int wave_s) {
;     ...
;             PG8_WAIT_V(8); PG8_WAIT_L(0); PG8_BAR; PG8_MMA(1, 0, At, B0); PG8_MMA(1, 1, At, B1); PG8_BAR; PG8_SCHED;
;             PG8_LDB(B0, 1, 0); PG8_LDB(B1, 1, 1); PG8_SCHED; PG8_LDA(At, 1, 0); PG8_STAGE(PG8_SA(0, 1), a2 + hstep, voffA);
;             PG8_WAIT_V(8); PG8_WAIT_L(0); PG8_BAR; PG8_MMA(0, 0, At, B0); PG8_MMA(0, 1, At, B1); PG8_BAR; PG8_SCHED;
	s_setprio 1
	v_mfma_f32_16x16x32_bf16 v[102:105], v[122:125], v[182:185], v[102:105]
	v_mfma_f32_16x16x32_bf16 v[98:101], v[138:141], v[182:185], v[98:101]
	v_mfma_f32_16x16x32_bf16 v[94:97], v[122:125], v[190:193], v[94:97]
	v_mfma_f32_16x16x32_bf16 v[90:93], v[138:141], v[190:193], v[90:93]
	v_mfma_f32_16x16x32_bf16 v[86:89], v[122:125], v[198:201], v[86:89]
	v_mfma_f32_16x16x32_bf16 v[82:85], v[138:141], v[198:201], v[82:85]
	v_mfma_f32_16x16x32_bf16 v[78:81], v[122:125], v[218:221], v[78:81]
	v_mfma_f32_16x16x32_bf16 v[74:77], v[138:141], v[218:221], v[74:77]
	v_mfma_f32_16x16x32_bf16 v[102:105], v[126:129], v[186:189], v[102:105]
	v_mfma_f32_16x16x32_bf16 v[98:101], v[142:145], v[186:189], v[98:101]
	v_mfma_f32_16x16x32_bf16 v[94:97], v[126:129], v[194:197], v[94:97]
	v_mfma_f32_16x16x32_bf16 v[90:93], v[142:145], v[194:197], v[90:93]
	v_mfma_f32_16x16x32_bf16 v[86:89], v[126:129], v[214:217], v[86:89]
	v_mfma_f32_16x16x32_bf16 v[82:85], v[142:145], v[214:217], v[82:85]
	v_mfma_f32_16x16x32_bf16 v[78:81], v[126:129], v[222:225], v[78:81]
	v_mfma_f32_16x16x32_bf16 v[74:77], v[142:145], v[222:225], v[74:77]
	s_setprio 0
	s_setprio 1
	v_mfma_f32_16x16x32_bf16 v[38:41], v[146:149], v[182:185], v[38:41]
	v_mfma_f32_16x16x32_bf16 v[34:37], v[174:177], v[182:185], v[34:37]
	v_mfma_f32_16x16x32_bf16 v[30:33], v[146:149], v[190:193], v[30:33]
	v_mfma_f32_16x16x32_bf16 v[26:29], v[174:177], v[190:193], v[26:29]
	v_mfma_f32_16x16x32_bf16 v[22:25], v[146:149], v[198:201], v[22:25]
	v_mfma_f32_16x16x32_bf16 v[18:21], v[174:177], v[198:201], v[18:21]
	v_mfma_f32_16x16x32_bf16 v[14:17], v[146:149], v[218:221], v[14:17]
	v_mfma_f32_16x16x32_bf16 v[10:13], v[174:177], v[218:221], v[10:13]
	v_mfma_f32_16x16x32_bf16 v[38:41], v[150:153], v[186:189], v[38:41]
	v_mfma_f32_16x16x32_bf16 v[34:37], v[178:181], v[186:189], v[34:37]
	v_mfma_f32_16x16x32_bf16 v[30:33], v[150:153], v[194:197], v[30:33]
	v_mfma_f32_16x16x32_bf16 v[26:29], v[178:181], v[194:197], v[26:29]
	v_mfma_f32_16x16x32_bf16 v[22:25], v[150:153], v[214:217], v[22:25]
	v_mfma_f32_16x16x32_bf16 v[18:21], v[178:181], v[214:217], v[18:21]
	v_mfma_f32_16x16x32_bf16 v[14:17], v[150:153], v[222:225], v[14:17]
	v_mfma_f32_16x16x32_bf16 v[10:13], v[178:181], v[222:225], v[10:13]
	s_barrier
	s_setprio 0
	s_add_i32 s45, 0, 0x18000
	v_add_u32_e32 v0, s45, v203
	s_add_i32 s80, 0, 0x1c000
	ds_read_b128 v[122:125], v0
	ds_read_b128 v[126:129], v0 offset:1024
	ds_read_b128 v[138:141], v0 offset:2048
	ds_read_b128 v[142:145], v0 offset:3072
	v_add_u32_e32 v0, s80, v203
	ds_read_b128 v[146:149], v0
	ds_read_b128 v[150:153], v0 offset:1024
	ds_read_b128 v[174:177], v0 offset:2048
	ds_read_b128 v[178:181], v0 offset:3072
	s_add_u32 s10, s48, 0xb0000
	s_addc_u32 s11, s49, 0
	s_mov_b32 m0, s88
	v_lshl_add_u64 v[234:235], s[10:11], 0, v[168:169]
	ds_read_b128 v[182:185], v212 offset:32768
	ds_read_b128 v[186:189], v212 offset:33792
	ds_read_b128 v[190:193], v212 offset:34816
	ds_read_b128 v[194:197], v212 offset:35840
	ds_read_b128 v[198:201], v212 offset:36864
	ds_read_b128 v[214:217], v212 offset:37888
	ds_read_b128 v[218:221], v212 offset:38912
	ds_read_b128 v[222:225], v212 offset:39936
	global_load_lds_dwordx4 v[234:235], off
	v_lshl_add_u64 v[234:235], s[10:11], 0, v[164:165]
	s_mov_b32 m0, s89
	s_nop 0
	global_load_lds_dwordx4 v[234:235], off
	s_waitcnt vmcnt(8)
	s_waitcnt lgkmcnt(0)
	s_barrier
	s_setprio 1
	v_mfma_f32_16x16x32_bf16 v[6:9], v[122:125], v[182:185], v[6:9]
	v_mfma_f32_16x16x32_bf16 v[2:5], v[138:141], v[182:185], v[2:5]
	v_mfma_f32_16x16x32_bf16 v[134:137], v[122:125], v[190:193], v[134:137]
	v_mfma_f32_16x16x32_bf16 v[130:133], v[138:141], v[190:193], v[130:133]
	v_mfma_f32_16x16x32_bf16 v[118:121], v[122:125], v[198:201], v[118:121]
	v_mfma_f32_16x16x32_bf16 v[114:117], v[138:141], v[198:201], v[114:117]
	v_mfma_f32_16x16x32_bf16 v[110:113], v[122:125], v[218:221], v[110:113]
	v_mfma_f32_16x16x32_bf16 v[106:109], v[138:141], v[218:221], v[106:109]
	v_mfma_f32_16x16x32_bf16 v[6:9], v[126:129], v[186:189], v[6:9]
	v_mfma_f32_16x16x32_bf16 v[2:5], v[142:145], v[186:189], v[2:5]
	v_mfma_f32_16x16x32_bf16 v[134:137], v[126:129], v[194:197], v[134:137]
	v_mfma_f32_16x16x32_bf16 v[130:133], v[142:145], v[194:197], v[130:133]
	v_mfma_f32_16x16x32_bf16 v[118:121], v[126:129], v[214:217], v[118:121]
	v_mfma_f32_16x16x32_bf16 v[114:117], v[142:145], v[214:217], v[114:117]
	v_mfma_f32_16x16x32_bf16 v[110:113], v[126:129], v[222:225], v[110:113]
	v_mfma_f32_16x16x32_bf16 v[106:109], v[142:145], v[222:225], v[106:109]
	s_setprio 0
	s_setprio 1
	v_mfma_f32_16x16x32_bf16 v[70:73], v[146:149], v[182:185], v[70:73]
	v_mfma_f32_16x16x32_bf16 v[66:69], v[174:177], v[182:185], v[66:69]
	v_mfma_f32_16x16x32_bf16 v[62:65], v[146:149], v[190:193], v[62:65]
	v_mfma_f32_16x16x32_bf16 v[58:61], v[174:177], v[190:193], v[58:61]
	v_mfma_f32_16x16x32_bf16 v[54:57], v[146:149], v[198:201], v[54:57]
	v_mfma_f32_16x16x32_bf16 v[50:53], v[174:177], v[198:201], v[50:53]
	v_mfma_f32_16x16x32_bf16 v[46:49], v[146:149], v[218:221], v[46:49]
	v_mfma_f32_16x16x32_bf16 v[42:45], v[174:177], v[218:221], v[42:45]
	v_mfma_f32_16x16x32_bf16 v[70:73], v[150:153], v[186:189], v[70:73]
	v_mfma_f32_16x16x32_bf16 v[66:69], v[178:181], v[186:189], v[66:69]
	v_mfma_f32_16x16x32_bf16 v[62:65], v[150:153], v[194:197], v[62:65]
	v_mfma_f32_16x16x32_bf16 v[58:61], v[178:181], v[194:197], v[58:61]
	v_mfma_f32_16x16x32_bf16 v[54:57], v[150:153], v[214:217], v[54:57]
	v_mfma_f32_16x16x32_bf16 v[50:53], v[178:181], v[214:217], v[50:53]
	v_mfma_f32_16x16x32_bf16 v[46:49], v[150:153], v[222:225], v[46:49]
	v_mfma_f32_16x16x32_bf16 v[42:45], v[178:181], v[222:225], v[42:45]
	s_barrier
; #define PG8_STAGE(bufoff, gbase, voff) do { _Pragma("unroll") for (int _i = 0; _i < 2; ++_i) \
;         __builtin_amdgcn_global_load_lds((const unsigned*)((const char*)(gbase) + (voff)[_i]), (PG8_LAS unsigned*)(lds + (bufoff) + ldsw + _i * 8192), 16, 0, 0); } while (0)
; #define PG8_LDA(dst, b, h) do { _Pragma("unroll") for (int m = 0; m < 4; ++m) _Pragma("unroll") for (int k = 0; k < 2; ++k) dst[m][k] = *(const PG8_LAS bf16x8*)(lds + PG8_SA(b, h) + aoff + m * 2048 + k * 1024); } while (0)
; #define PG8_MMA(ai, bj, At, Bt) do { __builtin_amdgcn_s_setprio(1); _Pragma("unroll") for (int m = 0; m < 4; ++m) _Pragma("unroll") for (int n = 0; n < 2; ++n) _Pragma("unroll") for (int k = 0; k < 2; ++k) \
;         acc[ai][bj][m][n] = __builtin_amdgcn_mfma_f32_16x16x32_bf16(Bt[n][k], At[m][k], acc[ai][bj][m][n], 0, 0, 0); __builtin_amdgcn_s_setprio(0); } while (0)
; #define PG8_WAIT_V(n) asm volatile("s_waitcnt vmcnt(" #n ")" ::: "memory")
; #define PG8_WAIT_L(n) asm volatile("s_waitcnt lgkmcnt(" #n ")" ::: "memory")
; #define PG8_BAR __builtin_amdgcn_s_barrier()
; #define PG8_SCHED __builtin_amdgcn_sched_barrier(0)
; template <class Epi, class Sched, bool ALIGN_EPI = false, bool SP2 = false>
; __device__ __forceinline__ void gemm_phase(PG8_LAS unsigned char* lds, const Gemm g, const Sched& S, const Epi& E, const int wave_s) {
;     ...
;             PG8_LDA(At, 1, 1); PG8_STAGE(PG8_SB(1, 0), b3, voffB); PG8_STAGE(PG8_SB(1, 1), b3 + hstep, voffB); PG8_STAGE(PG8_SA(1, 0), a3, voffA);
;             PG8_WAIT_V(8); PG8_WAIT_L(0); PG8_BAR; PG8_MMA(1, 0, At, B0); PG8_MMA(1, 1, At, B1); PG8_BAR; PG8_SCHED;
;     ...
;         if constexpr (ALIGN_EPI) { if (wr == 0) PG8_BAR; }
	s_setprio 0
	s_add_i32 s10, s45, s44
	v_lshl_add_u64 v[226:227], v[226:227], 0, s[70:71]
	s_mov_b32 m0, s10
	ds_read_b128 v[182:185], v212 offset:49152
	ds_read_b128 v[186:189], v212 offset:50176
	ds_read_b128 v[190:193], v212 offset:51200
	ds_read_b128 v[194:197], v212 offset:52224
	ds_read_b128 v[198:201], v212 offset:53248
	ds_read_b128 v[214:217], v212 offset:54272
	ds_read_b128 v[218:221], v212 offset:55296
	ds_read_b128 v[222:225], v212 offset:56320
	global_load_lds_dwordx4 v[226:227], off
	s_add_i32 m0, s10, 0x2000
	s_add_u32 s10, s40, 0xb0080
	v_lshl_add_u64 v[226:227], v[228:229], 0, s[70:71]
	s_addc_u32 s11, s41, 0
	s_add_i32 s40, s80, s44
	global_load_lds_dwordx4 v[226:227], off
	v_lshl_add_u64 v[226:227], s[10:11], 0, v[166:167]
	s_mov_b32 m0, s40
	s_nop 0
	global_load_lds_dwordx4 v[226:227], off
	v_lshl_add_u64 v[226:227], s[10:11], 0, v[162:163]
	s_add_i32 m0, s40, 0x2000
	s_nop 0
	global_load_lds_dwordx4 v[226:227], off
	v_lshl_add_u64 v[226:227], v[230:231], 0, s[70:71]
	s_mov_b32 m0, s62
	s_nop 0
	global_load_lds_dwordx4 v[226:227], off
	v_lshl_add_u64 v[226:227], v[232:233], 0, s[70:71]
	s_mov_b32 m0, s68
	s_nop 0
	global_load_lds_dwordx4 v[226:227], off
	s_waitcnt vmcnt(8)
	s_waitcnt lgkmcnt(0)
	s_barrier
	s_setprio 1
	v_mfma_f32_16x16x32_bf16 v[102:105], v[122:125], v[182:185], v[102:105]
	v_mfma_f32_16x16x32_bf16 v[98:101], v[138:141], v[182:185], v[98:101]
	v_mfma_f32_16x16x32_bf16 v[94:97], v[122:125], v[190:193], v[94:97]
	v_mfma_f32_16x16x32_bf16 v[90:93], v[138:141], v[190:193], v[90:93]
	v_mfma_f32_16x16x32_bf16 v[86:89], v[122:125], v[198:201], v[86:89]
	v_mfma_f32_16x16x32_bf16 v[82:85], v[138:141], v[198:201], v[82:85]
	v_mfma_f32_16x16x32_bf16 v[78:81], v[122:125], v[218:221], v[78:81]
	v_mfma_f32_16x16x32_bf16 v[74:77], v[138:141], v[218:221], v[74:77]
	v_mfma_f32_16x16x32_bf16 v[102:105], v[126:129], v[186:189], v[102:105]
	v_mfma_f32_16x16x32_bf16 v[98:101], v[142:145], v[186:189], v[98:101]
	v_mfma_f32_16x16x32_bf16 v[94:97], v[126:129], v[194:197], v[94:97]
	v_mfma_f32_16x16x32_bf16 v[90:93], v[142:145], v[194:197], v[90:93]
	v_mfma_f32_16x16x32_bf16 v[86:89], v[126:129], v[214:217], v[86:89]
	v_mfma_f32_16x16x32_bf16 v[82:85], v[142:145], v[214:217], v[82:85]
	v_mfma_f32_16x16x32_bf16 v[78:81], v[126:129], v[222:225], v[78:81]
	v_mfma_f32_16x16x32_bf16 v[74:77], v[142:145], v[222:225], v[74:77]
	s_setprio 0
	s_setprio 1
	v_mfma_f32_16x16x32_bf16 v[38:41], v[146:149], v[182:185], v[38:41]
	v_mfma_f32_16x16x32_bf16 v[34:37], v[174:177], v[182:185], v[34:37]
	v_mfma_f32_16x16x32_bf16 v[30:33], v[146:149], v[190:193], v[30:33]
	v_mfma_f32_16x16x32_bf16 v[26:29], v[174:177], v[190:193], v[26:29]
	v_mfma_f32_16x16x32_bf16 v[22:25], v[146:149], v[198:201], v[22:25]
	v_mfma_f32_16x16x32_bf16 v[18:21], v[174:177], v[198:201], v[18:21]
	v_mfma_f32_16x16x32_bf16 v[14:17], v[146:149], v[218:221], v[14:17]
	v_mfma_f32_16x16x32_bf16 v[10:13], v[174:177], v[218:221], v[10:13]
	v_mfma_f32_16x16x32_bf16 v[38:41], v[150:153], v[186:189], v[38:41]
	v_mfma_f32_16x16x32_bf16 v[34:37], v[178:181], v[186:189], v[34:37]
	v_mfma_f32_16x16x32_bf16 v[30:33], v[150:153], v[194:197], v[30:33]
	v_mfma_f32_16x16x32_bf16 v[26:29], v[178:181], v[194:197], v[26:29]
	v_mfma_f32_16x16x32_bf16 v[22:25], v[150:153], v[214:217], v[22:25]
	v_mfma_f32_16x16x32_bf16 v[18:21], v[178:181], v[214:217], v[18:21]
	v_mfma_f32_16x16x32_bf16 v[14:17], v[150:153], v[222:225], v[14:17]
	v_mfma_f32_16x16x32_bf16 v[10:13], v[178:181], v[222:225], v[10:13]
	s_barrier
	s_setprio 0
	s_add_i32 s75, s75, 2
	s_add_u32 vcc_lo, vcc_lo, 0x100
	s_addc_u32 vcc_hi, vcc_hi, 0
	s_cmp_gt_u32 s75, 41
	s_mov_b64 s[10:11], s[8:9]
	s_cbranch_scc0 .LBB0_806
	s_and_b64 vcc, exec, s[28:29]
	s_cbranch_vccz .LBB0_809
	s_barrier
